# gemm256 K-loop: top-of-step LDS reads issued in first-use order with incremental waits
# speedup vs baseline: 1.0438x; 1.0438x over previous
; #define GLDS_STAGE(st, kt_) do { \
;         _Pragma("unroll") for (int i_ = 0; i_ < FI; ++i_) { \
;             glds16(ap + (size_t)(32 * i_) * lda + (kt_) * 64, l3a + (st) + tid * 16 + i_ * 4096); \
;             glds16(bp + (size_t)(32 * i_) * ldb + (kt_) * 64, l3a + (st) + OPB + tid * 16 + i_ * 4096); } } while (0)
; #define GLDS_STAGE(st, kt_) do { \
;         _Pragma("unroll") for (int i_ = 0; i_ < 4; ++i_) { \
;             glds16(ap + (size_t)(64 * i_) * lda + (kt_) * 64, l3a + (st) + tid * 16 + i_ * 8192); \
;             glds16(bp + (size_t)(64 * i_) * ldb + (kt_) * 64, l3a + (st) + 32768 + tid * 16 + i_ * 8192); } } while (0)
; template <class Epi>
; DEV void gemm256_tile(const bf16_t* __restrict__ A, int lda, const bf16_t* __restrict__ Bt, int ldb, int K, unsigned char* lds, const Epi& epi) {
;     ...
;     for (int kt = 0; kt < nk; ++kt) {
;         const int cur = (kt & 1) * 65536;
;         asm volatile("s_waitcnt vmcnt(0)" ::: "memory");
;         __syncthreads();
;         if (kt + 1 < nk) GLDS_STAGE(cur ^ 65536, kt + 1);
; #pragma unroll
;         for (int kh = 0; kh < 2; ++kh) {
;             bf16x8 bfr[4];
;             const int ch = ((kh * 4 + fq) ^ sw) << 4;
; #pragma unroll
;             for (int i = 0; i < 4; ++i) bfr[i] = *(const bf16x8*)(lds + cur + boff + i * 2048 + ch);
; #pragma unroll
;             for (int mh = 0; mh < 2; ++mh) {
;                 bf16x8 af[4];
; #pragma unroll
;                 for (int i = 0; i < 4; ++i) af[i] = *(const bf16x8*)(lds + cur + aoff + (mh * 4 + i) * 2048 + ch);
; #pragma unroll
;                 for (int mi = 0; mi < 4; ++mi)
; #pragma unroll
;                     for (int ni = 0; ni < 4; ++ni) acc[mh * 4 + mi][ni] = __builtin_amdgcn_mfma_f32_16x16x32_bf16(bfr[ni], af[mi], acc[mh * 4 + mi][ni], 0, 0, 0);
;             }
;         }
;     }
.LBB0_174:
	s_and_b32 s48, s21, 0x10000
	s_xor_b32 s49, s48, 0x10000
	v_add_u32_e32 v216, s49, v142
	v_add_u32_e32 v217, s49, v156
	s_waitcnt vmcnt(0) lgkmcnt(0)
	s_barrier
	v_or_b32_e32 v248, s48, v175
	v_add_u32_e32 v249, s48, v157
	v_add_u32_e32 v244, v248, v174
	v_add_u32_e32 v245, v249, v174
	ds_read_b128 v[176:179], v244 offset:32768
	ds_read_b128 v[228:231], v245
	ds_read_b128 v[180:183], v244 offset:34816
	ds_read_b128 v[184:187], v244 offset:36864
	ds_read_b128 v[188:191], v244 offset:38912
	ds_read_b128 v[232:235], v245 offset:2048
	ds_read_b128 v[236:239], v245 offset:4096
	ds_read_b128 v[240:243], v245 offset:6144
	v_readfirstlane_b32 s40, v216
	v_readfirstlane_b32 s44, v217
	v_add_u32_e32 v246, v248, v155
	v_add_u32_e32 v247, v249, v155
	s_mov_b32 m0, s40
	v_lshl_add_u64 v[204:205], v[144:145], 0, s[4:5]
	global_load_lds_dwordx4 v[144:145], off
	s_mov_b32 m0, s44
	v_lshl_add_u64 v[210:211], v[146:147], 0, s[4:5]
	global_load_lds_dwordx4 v[146:147], off
	s_add_i32 s41, s40, 0x2000
	s_add_i32 s45, s44, 0x2000
	s_add_i32 s42, s40, 0x4000
	s_add_i32 s46, s44, 0x4000
	s_add_i32 s43, s40, 0x6000
	s_add_i32 s47, s44, 0x6000
	s_add_i32 s21, s21, 0x10000
	s_waitcnt lgkmcnt(6)
	v_mfma_f32_16x16x32_bf16 v[126:129], v[176:179], v[228:231], v[126:129]
	v_lshl_add_u64 v[206:207], v[144:145], 0, s[6:7]
	s_waitcnt lgkmcnt(5)
	v_mfma_f32_16x16x32_bf16 v[122:125], v[180:183], v[228:231], v[122:125]
	v_lshl_add_u64 v[212:213], v[146:147], 0, s[6:7]
	s_waitcnt lgkmcnt(4)
	v_mfma_f32_16x16x32_bf16 v[118:121], v[184:187], v[228:231], v[118:121]
	v_lshl_add_u64 v[208:209], v[144:145], 0, s[8:9]
	s_waitcnt lgkmcnt(3)
	v_mfma_f32_16x16x32_bf16 v[114:117], v[188:191], v[228:231], v[114:117]
	v_lshl_add_u64 v[214:215], v[146:147], 0, s[8:9]
	s_waitcnt lgkmcnt(2)
	v_mfma_f32_16x16x32_bf16 v[110:113], v[176:179], v[232:235], v[110:113]
	v_mfma_f32_16x16x32_bf16 v[106:109], v[180:183], v[232:235], v[106:109]
	v_mfma_f32_16x16x32_bf16 v[102:105], v[184:187], v[232:235], v[102:105]
	v_mfma_f32_16x16x32_bf16 v[98:101], v[188:191], v[232:235], v[98:101]
	s_waitcnt lgkmcnt(1)
	v_mfma_f32_16x16x32_bf16 v[94:97], v[176:179], v[236:239], v[94:97]
	ds_read_b128 v[228:231], v245 offset:8192
	v_mfma_f32_16x16x32_bf16 v[90:93], v[180:183], v[236:239], v[90:93]
	ds_read_b128 v[232:235], v245 offset:10240
	v_mfma_f32_16x16x32_bf16 v[86:89], v[184:187], v[236:239], v[86:89]
	s_mov_b32 m0, s41
	v_mfma_f32_16x16x32_bf16 v[82:85], v[188:191], v[236:239], v[82:85]
	global_load_lds_dwordx4 v[204:205], off
	s_waitcnt lgkmcnt(2)
	v_mfma_f32_16x16x32_bf16 v[78:81], v[176:179], v[240:243], v[78:81]
	s_mov_b32 m0, s45
	v_mfma_f32_16x16x32_bf16 v[74:77], v[180:183], v[240:243], v[74:77]
	global_load_lds_dwordx4 v[210:211], off
	v_mfma_f32_16x16x32_bf16 v[70:73], v[184:187], v[240:243], v[70:73]
	v_mfma_f32_16x16x32_bf16 v[66:69], v[188:191], v[240:243], v[66:69]
	s_waitcnt lgkmcnt(1)
	v_mfma_f32_16x16x32_bf16 v[62:65], v[176:179], v[228:231], v[62:65]
	ds_read_b128 v[236:239], v245 offset:12288
	v_mfma_f32_16x16x32_bf16 v[58:61], v[180:183], v[228:231], v[58:61]
	ds_read_b128 v[240:243], v245 offset:14336
	v_mfma_f32_16x16x32_bf16 v[54:57], v[184:187], v[228:231], v[54:57]
	s_mov_b32 m0, s42
	v_mfma_f32_16x16x32_bf16 v[50:53], v[188:191], v[228:231], v[50:53]
	global_load_lds_dwordx4 v[206:207], off
	s_waitcnt lgkmcnt(2)
	v_mfma_f32_16x16x32_bf16 v[46:49], v[176:179], v[232:235], v[46:49]
	s_mov_b32 m0, s46
	v_mfma_f32_16x16x32_bf16 v[42:45], v[180:183], v[232:235], v[42:45]
	global_load_lds_dwordx4 v[212:213], off
	v_mfma_f32_16x16x32_bf16 v[34:37], v[184:187], v[232:235], v[34:37]
	v_mfma_f32_16x16x32_bf16 v[30:33], v[188:191], v[232:235], v[30:33]
	s_waitcnt lgkmcnt(1)
	v_mfma_f32_16x16x32_bf16 v[26:29], v[176:179], v[236:239], v[26:29]
	ds_read_b128 v[192:195], v246 offset:32768
	v_mfma_f32_16x16x32_bf16 v[22:25], v[180:183], v[236:239], v[22:25]
	ds_read_b128 v[196:199], v246 offset:34816
	v_mfma_f32_16x16x32_bf16 v[18:21], v[184:187], v[236:239], v[18:21]
	ds_read_b128 v[220:223], v246 offset:36864
	v_mfma_f32_16x16x32_bf16 v[14:17], v[188:191], v[236:239], v[14:17]
	ds_read_b128 v[224:227], v246 offset:38912
	s_waitcnt lgkmcnt(4)
	v_mfma_f32_16x16x32_bf16 v[10:13], v[176:179], v[240:243], v[10:13]
	ds_read_b128 v[228:231], v247
	v_mfma_f32_16x16x32_bf16 v[6:9], v[180:183], v[240:243], v[6:9]
	ds_read_b128 v[232:235], v247 offset:2048
	v_mfma_f32_16x16x32_bf16 v[2:5], v[184:187], v[240:243], v[2:5]
	s_mov_b32 m0, s43
	v_mfma_f32_16x16x32_bf16 v[38:41], v[188:191], v[240:243], v[38:41]
	global_load_lds_dwordx4 v[208:209], off
	s_mov_b32 m0, s47
	v_lshl_add_u64 v[144:145], v[144:145], 0, s[10:11]
	global_load_lds_dwordx4 v[214:215], off
	v_lshl_add_u64 v[146:147], v[146:147], 0, s[10:11]
	s_waitcnt lgkmcnt(1)
	v_mfma_f32_16x16x32_bf16 v[126:129], v[192:195], v[228:231], v[126:129]
	ds_read_b128 v[236:239], v247 offset:4096
	v_mfma_f32_16x16x32_bf16 v[122:125], v[196:199], v[228:231], v[122:125]
	ds_read_b128 v[240:243], v247 offset:6144
	v_mfma_f32_16x16x32_bf16 v[118:121], v[220:223], v[228:231], v[118:121]
	v_mfma_f32_16x16x32_bf16 v[114:117], v[224:227], v[228:231], v[114:117]
	s_waitcnt lgkmcnt(2)
	v_mfma_f32_16x16x32_bf16 v[110:113], v[192:195], v[232:235], v[110:113]
	v_mfma_f32_16x16x32_bf16 v[106:109], v[196:199], v[232:235], v[106:109]
	v_mfma_f32_16x16x32_bf16 v[102:105], v[220:223], v[232:235], v[102:105]
	v_mfma_f32_16x16x32_bf16 v[98:101], v[224:227], v[232:235], v[98:101]
	s_waitcnt lgkmcnt(1)
; DEV unsigned cvt_pk_bf16(float lo, float hi) { const f32x2_t v = {lo, hi}; const bf16x2_t b = __builtin_convertvector(v, bf16x2_t); return __builtin_bit_cast(unsigned, b); }
; #define GLDS_STAGE(st, kt_) do { \
;         _Pragma("unroll") for (int i_ = 0; i_ < FI; ++i_) { \
;             glds16(ap + (size_t)(32 * i_) * lda + (kt_) * 64, l3a + (st) + tid * 16 + i_ * 4096); \
;             glds16(bp + (size_t)(32 * i_) * ldb + (kt_) * 64, l3a + (st) + OPB + tid * 16 + i_ * 4096); } } while (0)
; template <class Epi>
; DEV void gemm256_tile(const bf16_t* __restrict__ A, int lda, const bf16_t* __restrict__ Bt, int ldb, int K, unsigned char* lds, const Epi& epi) {
;     ...
;     for (int kt = 0; kt < nk; ++kt) {
;         const int cur = (kt & 1) * 65536;
;         asm volatile("s_waitcnt vmcnt(0)" ::: "memory");
;         __syncthreads();
;         if (kt + 1 < nk) GLDS_STAGE(cur ^ 65536, kt + 1);
; #pragma unroll
;         for (int kh = 0; kh < 2; ++kh) {
;             bf16x8 bfr[4];
;             const int ch = ((kh * 4 + fq) ^ sw) << 4;
; #pragma unroll
;             for (int i = 0; i < 4; ++i) bfr[i] = *(const bf16x8*)(lds + cur + boff + i * 2048 + ch);
; #pragma unroll
;             for (int mh = 0; mh < 2; ++mh) {
;                 bf16x8 af[4];
; #pragma unroll
;                 for (int i = 0; i < 4; ++i) af[i] = *(const bf16x8*)(lds + cur + aoff + (mh * 4 + i) * 2048 + ch);
; #pragma unroll
;                 for (int mi = 0; mi < 4; ++mi)
; #pragma unroll
;                     for (int ni = 0; ni < 4; ++ni) acc[mh * 4 + mi][ni] = __builtin_amdgcn_mfma_f32_16x16x32_bf16(bfr[ni], af[mi], acc[mh * 4 + mi][ni], 0, 0, 0);
;             }
;         }
;     }
;     ...
;     __syncthreads();
;     if constexpr (Epi::STAGE) {
; #pragma unroll
;         for (int mi = 0; mi < 8; ++mi)
; #pragma unroll
;             for (int ni = 0; ni < 4; ++ni) {
;                 const int row = wr * 128 + mi * 16 + fr, col = wc * 64 + ni * 16 + fq * 4;
;                 const f32x4 v = epi.xform(row, col, acc[mi][ni]);
;                 uint2 w; w.x = cvt_pk_bf16(v[0], v[1]); w.y = cvt_pk_bf16(v[2], v[3]);
;                 *(uint2*)(lds + row * 512 + ((((col >> 3) ^ (row & 31)) << 4) | (((col >> 2) & 1) << 3))) = w;
	v_mfma_f32_16x16x32_bf16 v[94:97], v[192:195], v[236:239], v[94:97]
	ds_read_b128 v[228:231], v247 offset:8192
	v_mfma_f32_16x16x32_bf16 v[90:93], v[196:199], v[236:239], v[90:93]
	ds_read_b128 v[232:235], v247 offset:10240
	v_mfma_f32_16x16x32_bf16 v[86:89], v[220:223], v[236:239], v[86:89]
	v_mfma_f32_16x16x32_bf16 v[82:85], v[224:227], v[236:239], v[82:85]
	s_waitcnt lgkmcnt(2)
	v_mfma_f32_16x16x32_bf16 v[78:81], v[192:195], v[240:243], v[78:81]
	v_mfma_f32_16x16x32_bf16 v[74:77], v[196:199], v[240:243], v[74:77]
	v_mfma_f32_16x16x32_bf16 v[70:73], v[220:223], v[240:243], v[70:73]
	v_mfma_f32_16x16x32_bf16 v[66:69], v[224:227], v[240:243], v[66:69]
	s_waitcnt lgkmcnt(1)
	v_mfma_f32_16x16x32_bf16 v[62:65], v[192:195], v[228:231], v[62:65]
	ds_read_b128 v[236:239], v247 offset:12288
	v_mfma_f32_16x16x32_bf16 v[58:61], v[196:199], v[228:231], v[58:61]
	ds_read_b128 v[240:243], v247 offset:14336
	v_mfma_f32_16x16x32_bf16 v[54:57], v[220:223], v[228:231], v[54:57]
	v_mfma_f32_16x16x32_bf16 v[50:53], v[224:227], v[228:231], v[50:53]
	s_waitcnt lgkmcnt(2)
	v_mfma_f32_16x16x32_bf16 v[46:49], v[192:195], v[232:235], v[46:49]
	v_mfma_f32_16x16x32_bf16 v[42:45], v[196:199], v[232:235], v[42:45]
	v_mfma_f32_16x16x32_bf16 v[34:37], v[220:223], v[232:235], v[34:37]
	v_mfma_f32_16x16x32_bf16 v[30:33], v[224:227], v[232:235], v[30:33]
	s_waitcnt lgkmcnt(1)
	v_mfma_f32_16x16x32_bf16 v[26:29], v[192:195], v[236:239], v[26:29]
	v_mfma_f32_16x16x32_bf16 v[22:25], v[196:199], v[236:239], v[22:25]
	v_mfma_f32_16x16x32_bf16 v[18:21], v[220:223], v[236:239], v[18:21]
	v_mfma_f32_16x16x32_bf16 v[14:17], v[224:227], v[236:239], v[14:17]
	s_waitcnt lgkmcnt(0)
	v_mfma_f32_16x16x32_bf16 v[10:13], v[192:195], v[240:243], v[10:13]
	v_mfma_f32_16x16x32_bf16 v[6:9], v[196:199], v[240:243], v[6:9]
	v_mfma_f32_16x16x32_bf16 v[2:5], v[220:223], v[240:243], v[2:5]
	v_mfma_f32_16x16x32_bf16 v[38:41], v[224:227], v[240:243], v[38:41]
	s_cmp_eq_u32 s21, 0x1f0000
	s_cbranch_scc0 .LBB0_174
	v_or_b32_e32 v156, 0x18000, v175
	v_add_u32_e32 v157, 0x10000, v157
	v_add_u32_e32 v186, v156, v174
	v_add_u32_e32 v194, v157, v174
	s_waitcnt vmcnt(0)
	s_barrier
	ds_read_b128 v[144:147], v186
	ds_read_b128 v[178:181], v186 offset:2048
	ds_read_b128 v[174:177], v194
	ds_read_b128 v[182:185], v186 offset:4096
	ds_read_b128 v[186:189], v186 offset:6144
	s_waitcnt lgkmcnt(2)
	v_mfma_f32_16x16x32_bf16 v[126:129], v[144:147], v[174:177], v[126:129]
	s_sext_i32_i16 s20, s20
	s_lshl_b32 s20, s20, 8
	s_ashr_i32 s21, s20, 31
	v_mfma_f32_16x16x32_bf16 v[122:125], v[178:181], v[174:177], v[122:125]
	s_waitcnt lgkmcnt(1)
	v_mfma_f32_16x16x32_bf16 v[118:121], v[182:185], v[174:177], v[118:121]
	s_waitcnt lgkmcnt(0)
	v_mfma_f32_16x16x32_bf16 v[114:117], v[186:189], v[174:177], v[114:117]
	ds_read_b128 v[174:177], v194 offset:2048
	s_waitcnt lgkmcnt(0)
	v_mfma_f32_16x16x32_bf16 v[110:113], v[144:147], v[174:177], v[110:113]
	v_mfma_f32_16x16x32_bf16 v[106:109], v[178:181], v[174:177], v[106:109]
	v_mfma_f32_16x16x32_bf16 v[102:105], v[182:185], v[174:177], v[102:105]
	v_mfma_f32_16x16x32_bf16 v[98:101], v[186:189], v[174:177], v[98:101]
	ds_read_b128 v[174:177], v194 offset:4096
	s_waitcnt lgkmcnt(0)
	v_mfma_f32_16x16x32_bf16 v[94:97], v[144:147], v[174:177], v[94:97]
	v_mfma_f32_16x16x32_bf16 v[90:93], v[178:181], v[174:177], v[90:93]
	v_mfma_f32_16x16x32_bf16 v[86:89], v[182:185], v[174:177], v[86:89]
	v_mfma_f32_16x16x32_bf16 v[82:85], v[186:189], v[174:177], v[82:85]
	ds_read_b128 v[174:177], v194 offset:6144
	s_waitcnt lgkmcnt(0)
	v_mfma_f32_16x16x32_bf16 v[78:81], v[144:147], v[174:177], v[78:81]
	v_mfma_f32_16x16x32_bf16 v[74:77], v[178:181], v[174:177], v[74:77]
	v_mfma_f32_16x16x32_bf16 v[70:73], v[182:185], v[174:177], v[70:73]
	v_mfma_f32_16x16x32_bf16 v[66:69], v[186:189], v[174:177], v[66:69]
	ds_read_b128 v[174:177], v194 offset:8192
	ds_read_b128 v[190:193], v194 offset:10240
	s_waitcnt lgkmcnt(1)
	v_mfma_f32_16x16x32_bf16 v[62:65], v[144:147], v[174:177], v[62:65]
	v_mfma_f32_16x16x32_bf16 v[58:61], v[178:181], v[174:177], v[58:61]
	v_mfma_f32_16x16x32_bf16 v[54:57], v[182:185], v[174:177], v[54:57]
	v_mfma_f32_16x16x32_bf16 v[50:53], v[186:189], v[174:177], v[50:53]
	ds_read_b128 v[174:177], v194 offset:12288
	s_waitcnt lgkmcnt(1)
	v_mfma_f32_16x16x32_bf16 v[46:49], v[144:147], v[190:193], v[46:49]
	v_mfma_f32_16x16x32_bf16 v[42:45], v[178:181], v[190:193], v[42:45]
	v_mfma_f32_16x16x32_bf16 v[34:37], v[182:185], v[190:193], v[34:37]
	v_mfma_f32_16x16x32_bf16 v[30:33], v[186:189], v[190:193], v[30:33]
	ds_read_b128 v[190:193], v194 offset:14336
	s_waitcnt lgkmcnt(1)
	v_mfma_f32_16x16x32_bf16 v[194:197], v[144:147], v[174:177], v[26:29]
	s_nop 2
	v_add_u32_e32 v29, v156, v155
	ds_read_b128 v[198:201], v29
	ds_read_b128 v[202:205], v29 offset:2048
	ds_read_b128 v[206:209], v29 offset:4096
	ds_read_b128 v[210:213], v29 offset:6144
	v_add_u32_e32 v29, v157, v155
	v_mfma_f32_16x16x32_bf16 v[22:25], v[178:181], v[174:177], v[22:25]
	v_and_b32_e32 v28, 0xc0, v150
	v_lshl_or_b32 v153, v153, 2, v28
	v_lshlrev_b32_e32 v28, 3, v152
	v_mfma_f32_16x16x32_bf16 v[18:21], v[182:185], v[174:177], v[18:21]
	v_mad_i64_i32 v[26:27], s[22:23], s19, v149, v[172:173]
	v_lshl_add_u64 v[26:27], s[20:21], 1, v[26:27]
	v_mfma_f32_16x16x32_bf16 v[14:17], v[186:189], v[174:177], v[14:17]
	ds_read_b128 v[174:177], v29
	ds_read_b128 v[214:217], v29 offset:2048
	ds_read_b128 v[218:221], v29 offset:4096
	ds_read_b128 v[222:225], v29 offset:6144
	s_mov_b32 s19, 0
	s_waitcnt lgkmcnt(3)
	v_mfma_f32_16x16x32_bf16 v[126:129], v[198:201], v[174:177], v[126:129]
	v_mfma_f32_16x16x32_bf16 v[122:125], v[202:205], v[174:177], v[122:125]
	s_waitcnt lgkmcnt(1)
	v_mfma_f32_16x16x32_bf16 v[94:97], v[198:201], v[218:221], v[94:97]
	v_mfma_f32_16x16x32_bf16 v[10:13], v[144:147], v[190:193], v[10:13]
	ds_read_b128 v[144:147], v29 offset:8192
	ds_read_b128 v[226:229], v29 offset:10240
	ds_read_b128 v[230:233], v29 offset:12288
	ds_read_b128 v[234:237], v29 offset:14336
	v_lshlrev_b32_e32 v29, 9, v154
	v_and_or_b32 v152, v28, 8, v29
	v_mfma_f32_16x16x32_bf16 v[118:121], v[206:209], v[174:177], v[118:121]
	v_cvt_pk_bf16_f32 v28, v126, v127
	v_lshrrev_b32_e32 v126, 3, v153
	v_xor_b32_e32 v127, v126, v151
	v_mfma_f32_16x16x32_bf16 v[90:93], v[202:205], v[218:221], v[90:93]
	v_cvt_pk_bf16_f32 v29, v128, v129
	v_lshl_or_b32 v127, v127, 4, v152
	v_cvt_pk_bf16_f32 v122, v122, v123
	v_mfma_f32_16x16x32_bf16 v[114:117], v[210:213], v[174:177], v[114:117]
	v_cvt_pk_bf16_f32 v123, v124, v125
	v_bitop3_b32 v124, v126, v151, 2 bitop3:0x36
	v_cvt_pk_bf16_f32 v94, v94, v95
	v_mfma_f32_16x16x32_bf16 v[86:89], v[206:209], v[218:221], v[86:89]
	v_cvt_pk_bf16_f32 v95, v96, v97
	s_waitcnt lgkmcnt(0)
	s_barrier
; DEV unsigned cvt_pk_bf16(float lo, float hi) { const f32x2_t v = {lo, hi}; const bf16x2_t b = __builtin_convertvector(v, bf16x2_t); return __builtin_bit_cast(unsigned, b); }
; template <class Epi>
; DEV void gemm256_tile(const bf16_t* __restrict__ A, int lda, const bf16_t* __restrict__ Bt, int ldb, int K, unsigned char* lds, const Epi& epi) {
;     ...
;     if constexpr (Epi::STAGE) {
; #pragma unroll
;         for (int mi = 0; mi < 8; ++mi)
; #pragma unroll
;             for (int ni = 0; ni < 4; ++ni) {
;                 const int row = wr * 128 + mi * 16 + fr, col = wc * 64 + ni * 16 + fq * 4;
;                 const f32x4 v = epi.xform(row, col, acc[mi][ni]);
;                 uint2 w; w.x = cvt_pk_bf16(v[0], v[1]); w.y = cvt_pk_bf16(v[2], v[3]);
;                 *(uint2*)(lds + row * 512 + ((((col >> 3) ^ (row & 31)) << 4) | (((col >> 2) & 1) << 3))) = w;
;             }
;         __syncthreads();
	v_mfma_f32_16x16x32_bf16 v[110:113], v[198:201], v[214:217], v[110:113]
	v_lshl_add_u32 v124, v124, 4, v152
	v_cvt_pk_bf16_f32 v118, v118, v119
	v_mfma_f32_16x16x32_bf16 v[82:85], v[210:213], v[218:221], v[82:85]
	v_cvt_pk_bf16_f32 v119, v120, v121
	v_bitop3_b32 v120, v126, v151, 4 bitop3:0x36
	ds_write2st64_b64 v127, v[28:29], v[94:95] offset1:32
	v_mfma_f32_16x16x32_bf16 v[106:109], v[202:205], v[214:217], v[106:109]
	v_cvt_pk_bf16_f32 v28, v90, v91
	v_cvt_pk_bf16_f32 v29, v92, v93
	v_lshl_add_u32 v120, v120, 4, v152
	v_mfma_f32_16x16x32_bf16 v[78:81], v[198:201], v[222:225], v[78:81]
	v_cvt_pk_bf16_f32 v114, v114, v115
	v_cvt_pk_bf16_f32 v115, v116, v117
	v_bitop3_b32 v116, v126, v151, 6 bitop3:0x36
	v_mfma_f32_16x16x32_bf16 v[102:105], v[206:209], v[214:217], v[102:105]
	ds_write2st64_b64 v124, v[122:123], v[28:29] offset1:32
	v_cvt_pk_bf16_f32 v28, v86, v87
	v_cvt_pk_bf16_f32 v29, v88, v89
	v_mfma_f32_16x16x32_bf16 v[74:77], v[202:205], v[222:225], v[74:77]
	v_lshl_add_u32 v116, v116, 4, v152
	v_or_b32_e32 v117, 16, v151
	v_cvt_pk_bf16_f32 v110, v110, v111
	v_mfma_f32_16x16x32_bf16 v[2:5], v[182:185], v[190:193], v[2:5]
	v_cvt_pk_bf16_f32 v111, v112, v113
	v_bitop3_b32 v112, v126, v151, 16 bitop3:0x1e
	ds_write2st64_b64 v120, v[118:119], v[28:29] offset1:32
	v_mfma_f32_16x16x32_bf16 v[98:101], v[210:213], v[214:217], v[98:101]
	v_cvt_pk_bf16_f32 v28, v82, v83
	v_cvt_pk_bf16_f32 v29, v84, v85
	v_lshl_or_b32 v112, v112, 4, v152
	v_mfma_f32_16x16x32_bf16 v[70:73], v[206:209], v[222:225], v[70:73]
	v_cvt_pk_bf16_f32 v106, v106, v107
	v_cvt_pk_bf16_f32 v107, v108, v109
	v_bitop3_b32 v108, v126, v117, 2 bitop3:0x36
	v_mfma_f32_16x16x32_bf16 v[66:69], v[210:213], v[222:225], v[66:69]
	ds_write2st64_b64 v116, v[114:115], v[28:29] offset1:32
	v_cvt_pk_bf16_f32 v28, v78, v79
	v_cvt_pk_bf16_f32 v29, v80, v81
	v_lshl_add_u32 v108, v108, 4, v152
	v_cvt_pk_bf16_f32 v102, v102, v103
	v_cvt_pk_bf16_f32 v103, v104, v105
	v_bitop3_b32 v104, v126, v117, 4 bitop3:0x36
	ds_write2st64_b64 v112, v[110:111], v[28:29] offset0:16 offset1:48
	v_cvt_pk_bf16_f32 v28, v74, v75
	v_cvt_pk_bf16_f32 v29, v76, v77
	v_lshl_add_u32 v104, v104, 4, v152
	v_cvt_pk_bf16_f32 v98, v98, v99
	v_cvt_pk_bf16_f32 v99, v100, v101
	v_bitop3_b32 v100, v126, v117, 6 bitop3:0x36
	ds_write2st64_b64 v108, v[106:107], v[28:29] offset0:16 offset1:48
	v_cvt_pk_bf16_f32 v28, v70, v71
	v_cvt_pk_bf16_f32 v29, v72, v73
	v_mfma_f32_16x16x32_bf16 v[34:37], v[206:209], v[226:229], v[34:37]
	v_lshl_add_u32 v100, v100, 4, v152
	ds_write2st64_b64 v104, v[102:103], v[28:29] offset0:16 offset1:48
	v_cvt_pk_bf16_f32 v28, v66, v67
	v_mfma_f32_16x16x32_bf16 v[2:5], v[206:209], v[234:237], v[2:5]
	v_cvt_pk_bf16_f32 v29, v68, v69
	ds_write2st64_b64 v100, v[98:99], v[28:29] offset0:16 offset1:48
	s_nop 1
	v_cvt_pk_bf16_f32 v34, v34, v35
	v_mfma_f32_16x16x32_bf16 v[38:41], v[186:189], v[190:193], v[38:41]
	v_cvt_pk_bf16_f32 v35, v36, v37
	s_nop 0
	v_cvt_pk_bf16_f32 v2, v2, v3
	v_cvt_pk_bf16_f32 v3, v4, v5
	v_mfma_f32_16x16x32_bf16 v[6:9], v[178:181], v[190:193], v[6:9]
	ds_write2st64_b64 v104, v[34:35], v[2:3] offset0:80 offset1:112
	v_mfma_f32_16x16x32_bf16 v[28:31], v[210:213], v[226:229], v[30:33]
	v_mfma_f32_16x16x32_bf16 v[2:5], v[210:213], v[234:237], v[38:41]
	v_mfma_f32_16x16x32_bf16 v[62:65], v[198:201], v[144:147], v[62:65]
	s_nop 5
	v_cvt_pk_bf16_f32 v32, v28, v29
	v_cvt_pk_bf16_f32 v33, v30, v31
	v_cvt_pk_bf16_f32 v2, v2, v3
	v_mfma_f32_16x16x32_bf16 v[58:61], v[202:205], v[144:147], v[58:61]
	v_cvt_pk_bf16_f32 v3, v4, v5
	v_cvt_pk_bf16_f32 v62, v62, v63
	v_cvt_pk_bf16_f32 v63, v64, v65
	v_mfma_f32_16x16x32_bf16 v[54:57], v[206:209], v[144:147], v[54:57]
	ds_write2st64_b64 v100, v[32:33], v[2:3] offset0:80 offset1:112
	s_nop 2
	v_cvt_pk_bf16_f32 v58, v58, v59
	v_cvt_pk_bf16_f32 v59, v60, v61
	v_mfma_f32_16x16x32_bf16 v[50:53], v[210:213], v[144:147], v[50:53]
	v_and_b32_e32 v2, 0x1f0, v142
	v_cvt_pk_bf16_f32 v54, v54, v55
	v_cvt_pk_bf16_f32 v55, v56, v57
	v_mfma_f32_16x16x32_bf16 v[46:49], v[198:201], v[226:229], v[46:49]
	v_mfma_f32_16x16x32_bf16 v[42:45], v[202:205], v[226:229], v[42:45]
	s_nop 2
	v_cvt_pk_bf16_f32 v50, v50, v51
	v_cvt_pk_bf16_f32 v51, v52, v53
	s_nop 1
	v_cvt_pk_bf16_f32 v46, v46, v47
	v_mfma_f32_16x16x32_bf16 v[28:31], v[198:201], v[230:233], v[194:197]
	v_cvt_pk_bf16_f32 v47, v48, v49
	v_cvt_pk_bf16_f32 v42, v42, v43
	v_cvt_pk_bf16_f32 v43, v44, v45
	v_mfma_f32_16x16x32_bf16 v[22:25], v[202:205], v[230:233], v[22:25]
	v_mfma_f32_16x16x32_bf16 v[18:21], v[206:209], v[230:233], v[18:21]
	s_nop 2
	v_cvt_pk_bf16_f32 v28, v28, v29
	v_cvt_pk_bf16_f32 v29, v30, v31
	s_nop 1
	v_cvt_pk_bf16_f32 v22, v22, v23
	v_mfma_f32_16x16x32_bf16 v[14:17], v[210:213], v[230:233], v[14:17]
	v_cvt_pk_bf16_f32 v23, v24, v25
	v_cvt_pk_bf16_f32 v18, v18, v19
	v_cvt_pk_bf16_f32 v19, v20, v21
	v_mfma_f32_16x16x32_bf16 v[10:13], v[198:201], v[234:237], v[10:13]
	ds_write2st64_b64 v127, v[62:63], v[28:29] offset0:64 offset1:96
	s_nop 2
	v_cvt_pk_bf16_f32 v14, v14, v15
	v_cvt_pk_bf16_f32 v15, v16, v17
	v_mfma_f32_16x16x32_bf16 v[6:9], v[202:205], v[234:237], v[6:9]
	ds_write2st64_b64 v124, v[58:59], v[22:23] offset0:64 offset1:96
	v_cvt_pk_bf16_f32 v10, v10, v11
	v_cvt_pk_bf16_f32 v11, v12, v13
	ds_write2st64_b64 v120, v[54:55], v[18:19] offset0:64 offset1:96
	ds_write2st64_b64 v116, v[50:51], v[14:15] offset0:64 offset1:96
	s_nop 2
	v_cvt_pk_bf16_f32 v6, v6, v7
	v_cvt_pk_bf16_f32 v7, v8, v9
	ds_write2st64_b64 v112, v[46:47], v[10:11] offset0:80 offset1:112
	ds_write2st64_b64 v108, v[42:43], v[6:7] offset0:80 offset1:112
	s_waitcnt lgkmcnt(0)
	s_barrier

; #define GLDS_STAGE(st, kt_) do { \
;         _Pragma("unroll") for (int i_ = 0; i_ < FI; ++i_) { \
;             glds16(ap + (size_t)(32 * i_) * lda + (kt_) * 64, l3a + (st) + tid * 16 + i_ * 4096); \
;             glds16(bp + (size_t)(32 * i_) * ldb + (kt_) * 64, l3a + (st) + OPB + tid * 16 + i_ * 4096); } } while (0)
; #define GLDS_STAGE(st, kt_) do { \
;         _Pragma("unroll") for (int i_ = 0; i_ < 4; ++i_) { \
;             glds16(ap + (size_t)(64 * i_) * lda + (kt_) * 64, l3a + (st) + tid * 16 + i_ * 8192); \
;             glds16(bp + (size_t)(64 * i_) * ldb + (kt_) * 64, l3a + (st) + 32768 + tid * 16 + i_ * 8192); } } while (0)
; template <class Epi>
; DEV void gemm256_tile(const bf16_t* __restrict__ A, int lda, const bf16_t* __restrict__ Bt, int ldb, int K, unsigned char* lds, const Epi& epi) {
;     ...
;     for (int kt = 0; kt < nk; ++kt) {
;         const int cur = (kt & 1) * 65536;
;         asm volatile("s_waitcnt vmcnt(0)" ::: "memory");
;         __syncthreads();
;         if (kt + 1 < nk) GLDS_STAGE(cur ^ 65536, kt + 1);
; #pragma unroll
;         for (int kh = 0; kh < 2; ++kh) {
;             bf16x8 bfr[4];
;             const int ch = ((kh * 4 + fq) ^ sw) << 4;
; #pragma unroll
;             for (int i = 0; i < 4; ++i) bfr[i] = *(const bf16x8*)(lds + cur + boff + i * 2048 + ch);
; #pragma unroll
;             for (int mh = 0; mh < 2; ++mh) {
;                 bf16x8 af[4];
; #pragma unroll
;                 for (int i = 0; i < 4; ++i) af[i] = *(const bf16x8*)(lds + cur + aoff + (mh * 4 + i) * 2048 + ch);
; #pragma unroll
;                 for (int mi = 0; mi < 4; ++mi)
; #pragma unroll
;                     for (int ni = 0; ni < 4; ++ni) acc[mh * 4 + mi][ni] = __builtin_amdgcn_mfma_f32_16x16x32_bf16(bfr[ni], af[mi], acc[mh * 4 + mi][ni], 0, 0, 0);
;             }
;         }
;     }
.LBB0_1003:
	s_and_b32 s48, s25, 0x10000
	s_xor_b32 s49, s48, 0x10000
	v_add_u32_e32 v216, s49, v136
	v_add_u32_e32 v217, s49, v150
	s_waitcnt vmcnt(0) lgkmcnt(0)
	s_barrier
	v_or_b32_e32 v248, s48, v151
	v_add_u32_e32 v249, s48, v148
	v_add_u32_e32 v244, v248, v149
	v_add_u32_e32 v245, v249, v149
	ds_read_b128 v[152:155], v244 offset:32768
	ds_read_b128 v[228:231], v245
	ds_read_b128 v[176:179], v244 offset:34816
	ds_read_b128 v[180:183], v244 offset:36864
	ds_read_b128 v[184:187], v244 offset:38912
	ds_read_b128 v[232:235], v245 offset:2048
	ds_read_b128 v[236:239], v245 offset:4096
	ds_read_b128 v[240:243], v245 offset:6144
	v_readfirstlane_b32 s40, v216
	v_readfirstlane_b32 s44, v217
	v_add_u32_e32 v246, v248, v147
	v_add_u32_e32 v247, v249, v147
	s_mov_b32 m0, s40
	v_lshl_add_u64 v[204:205], v[138:139], 0, s[6:7]
	global_load_lds_dwordx4 v[138:139], off
	s_mov_b32 m0, s44
	v_lshl_add_u64 v[210:211], v[140:141], 0, s[6:7]
	global_load_lds_dwordx4 v[140:141], off
	s_add_i32 s41, s40, 0x2000
	s_add_i32 s45, s44, 0x2000
	s_add_i32 s42, s40, 0x4000
	s_add_i32 s46, s44, 0x4000
	s_add_i32 s43, s40, 0x6000
	s_add_i32 s47, s44, 0x6000
	s_add_i32 s25, s25, 0x10000
	s_waitcnt lgkmcnt(6)
	v_mfma_f32_16x16x32_bf16 v[126:129], v[152:155], v[228:231], v[126:129]
	v_lshl_add_u64 v[206:207], v[138:139], 0, s[8:9]
	s_waitcnt lgkmcnt(5)
	v_mfma_f32_16x16x32_bf16 v[122:125], v[176:179], v[228:231], v[122:125]
	v_lshl_add_u64 v[212:213], v[140:141], 0, s[8:9]
	s_waitcnt lgkmcnt(4)
	v_mfma_f32_16x16x32_bf16 v[118:121], v[180:183], v[228:231], v[118:121]
	v_lshl_add_u64 v[208:209], v[138:139], 0, s[10:11]
	s_waitcnt lgkmcnt(3)
	v_mfma_f32_16x16x32_bf16 v[114:117], v[184:187], v[228:231], v[114:117]
	v_lshl_add_u64 v[214:215], v[140:141], 0, s[10:11]
	s_waitcnt lgkmcnt(2)
	v_mfma_f32_16x16x32_bf16 v[110:113], v[152:155], v[232:235], v[110:113]
	v_mfma_f32_16x16x32_bf16 v[106:109], v[176:179], v[232:235], v[106:109]
	v_mfma_f32_16x16x32_bf16 v[102:105], v[180:183], v[232:235], v[102:105]
	v_mfma_f32_16x16x32_bf16 v[98:101], v[184:187], v[232:235], v[98:101]
	s_waitcnt lgkmcnt(1)
	v_mfma_f32_16x16x32_bf16 v[94:97], v[152:155], v[236:239], v[94:97]
	ds_read_b128 v[228:231], v245 offset:8192
	v_mfma_f32_16x16x32_bf16 v[90:93], v[176:179], v[236:239], v[90:93]
	ds_read_b128 v[232:235], v245 offset:10240
	v_mfma_f32_16x16x32_bf16 v[86:89], v[180:183], v[236:239], v[86:89]
	s_mov_b32 m0, s41
	v_mfma_f32_16x16x32_bf16 v[82:85], v[184:187], v[236:239], v[82:85]
	global_load_lds_dwordx4 v[204:205], off
	s_waitcnt lgkmcnt(2)
	v_mfma_f32_16x16x32_bf16 v[78:81], v[152:155], v[240:243], v[78:81]
	s_mov_b32 m0, s45
	v_mfma_f32_16x16x32_bf16 v[74:77], v[176:179], v[240:243], v[74:77]
	global_load_lds_dwordx4 v[210:211], off
	v_mfma_f32_16x16x32_bf16 v[70:73], v[180:183], v[240:243], v[70:73]
	v_mfma_f32_16x16x32_bf16 v[66:69], v[184:187], v[240:243], v[66:69]
	s_waitcnt lgkmcnt(1)
	v_mfma_f32_16x16x32_bf16 v[62:65], v[152:155], v[228:231], v[62:65]
	ds_read_b128 v[236:239], v245 offset:12288
	v_mfma_f32_16x16x32_bf16 v[58:61], v[176:179], v[228:231], v[58:61]
	ds_read_b128 v[240:243], v245 offset:14336
	v_mfma_f32_16x16x32_bf16 v[54:57], v[180:183], v[228:231], v[54:57]
	s_mov_b32 m0, s42
	v_mfma_f32_16x16x32_bf16 v[50:53], v[184:187], v[228:231], v[50:53]
	global_load_lds_dwordx4 v[206:207], off
	s_waitcnt lgkmcnt(2)
	v_mfma_f32_16x16x32_bf16 v[46:49], v[152:155], v[232:235], v[46:49]
	s_mov_b32 m0, s46
	v_mfma_f32_16x16x32_bf16 v[42:45], v[176:179], v[232:235], v[42:45]
	global_load_lds_dwordx4 v[212:213], off
	v_mfma_f32_16x16x32_bf16 v[34:37], v[180:183], v[232:235], v[34:37]
	v_mfma_f32_16x16x32_bf16 v[30:33], v[184:187], v[232:235], v[30:33]
	s_waitcnt lgkmcnt(1)
	v_mfma_f32_16x16x32_bf16 v[26:29], v[152:155], v[236:239], v[26:29]
	ds_read_b128 v[188:191], v246 offset:32768
	v_mfma_f32_16x16x32_bf16 v[22:25], v[176:179], v[236:239], v[22:25]
	ds_read_b128 v[192:195], v246 offset:34816
	v_mfma_f32_16x16x32_bf16 v[18:21], v[180:183], v[236:239], v[18:21]
	ds_read_b128 v[220:223], v246 offset:36864
	v_mfma_f32_16x16x32_bf16 v[14:17], v[184:187], v[236:239], v[14:17]
	ds_read_b128 v[224:227], v246 offset:38912
	s_waitcnt lgkmcnt(4)
	v_mfma_f32_16x16x32_bf16 v[10:13], v[152:155], v[240:243], v[10:13]
	ds_read_b128 v[228:231], v247
	v_mfma_f32_16x16x32_bf16 v[6:9], v[176:179], v[240:243], v[6:9]
	ds_read_b128 v[232:235], v247 offset:2048
	v_mfma_f32_16x16x32_bf16 v[2:5], v[180:183], v[240:243], v[2:5]
	s_mov_b32 m0, s43
	v_mfma_f32_16x16x32_bf16 v[38:41], v[184:187], v[240:243], v[38:41]
	global_load_lds_dwordx4 v[208:209], off
	s_mov_b32 m0, s47
	v_lshl_add_u64 v[138:139], v[138:139], 0, s[12:13]
	global_load_lds_dwordx4 v[214:215], off
	v_lshl_add_u64 v[140:141], v[140:141], 0, s[12:13]
	s_waitcnt lgkmcnt(1)
	v_mfma_f32_16x16x32_bf16 v[126:129], v[188:191], v[228:231], v[126:129]
	ds_read_b128 v[236:239], v247 offset:4096
	v_mfma_f32_16x16x32_bf16 v[122:125], v[192:195], v[228:231], v[122:125]
	ds_read_b128 v[240:243], v247 offset:6144
	v_mfma_f32_16x16x32_bf16 v[118:121], v[220:223], v[228:231], v[118:121]
	v_mfma_f32_16x16x32_bf16 v[114:117], v[224:227], v[228:231], v[114:117]
	s_waitcnt lgkmcnt(2)
	v_mfma_f32_16x16x32_bf16 v[110:113], v[188:191], v[232:235], v[110:113]
	v_mfma_f32_16x16x32_bf16 v[106:109], v[192:195], v[232:235], v[106:109]
	v_mfma_f32_16x16x32_bf16 v[102:105], v[220:223], v[232:235], v[102:105]
	v_mfma_f32_16x16x32_bf16 v[98:101], v[224:227], v[232:235], v[98:101]
	s_waitcnt lgkmcnt(1)
; DEV unsigned cvt_pk_bf16(float lo, float hi) { const f32x2_t v = {lo, hi}; const bf16x2_t b = __builtin_convertvector(v, bf16x2_t); return __builtin_bit_cast(unsigned, b); }
; #define GLDS_STAGE(st, kt_) do { \
;         _Pragma("unroll") for (int i_ = 0; i_ < FI; ++i_) { \
;             glds16(ap + (size_t)(32 * i_) * lda + (kt_) * 64, l3a + (st) + tid * 16 + i_ * 4096); \
;             glds16(bp + (size_t)(32 * i_) * ldb + (kt_) * 64, l3a + (st) + OPB + tid * 16 + i_ * 4096); } } while (0)
; template <class Epi>
; DEV void gemm256_tile(const bf16_t* __restrict__ A, int lda, const bf16_t* __restrict__ Bt, int ldb, int K, unsigned char* lds, const Epi& epi) {
;     ...
;     for (int kt = 0; kt < nk; ++kt) {
;         const int cur = (kt & 1) * 65536;
;         asm volatile("s_waitcnt vmcnt(0)" ::: "memory");
;         __syncthreads();
;         if (kt + 1 < nk) GLDS_STAGE(cur ^ 65536, kt + 1);
; #pragma unroll
;         for (int kh = 0; kh < 2; ++kh) {
;             bf16x8 bfr[4];
;             const int ch = ((kh * 4 + fq) ^ sw) << 4;
; #pragma unroll
;             for (int i = 0; i < 4; ++i) bfr[i] = *(const bf16x8*)(lds + cur + boff + i * 2048 + ch);
; #pragma unroll
;             for (int mh = 0; mh < 2; ++mh) {
;                 bf16x8 af[4];
; #pragma unroll
;                 for (int i = 0; i < 4; ++i) af[i] = *(const bf16x8*)(lds + cur + aoff + (mh * 4 + i) * 2048 + ch);
; #pragma unroll
;                 for (int mi = 0; mi < 4; ++mi)
; #pragma unroll
;                     for (int ni = 0; ni < 4; ++ni) acc[mh * 4 + mi][ni] = __builtin_amdgcn_mfma_f32_16x16x32_bf16(bfr[ni], af[mi], acc[mh * 4 + mi][ni], 0, 0, 0);
;             }
;         }
;     }
;     ...
;     __syncthreads();
;     if constexpr (Epi::STAGE) {
; #pragma unroll
;         for (int mi = 0; mi < 8; ++mi)
; #pragma unroll
;             for (int ni = 0; ni < 4; ++ni) {
;                 const int row = wr * 128 + mi * 16 + fr, col = wc * 64 + ni * 16 + fq * 4;
;                 const f32x4 v = epi.xform(row, col, acc[mi][ni]);
;                 uint2 w; w.x = cvt_pk_bf16(v[0], v[1]); w.y = cvt_pk_bf16(v[2], v[3]);
;                 *(uint2*)(lds + row * 512 + ((((col >> 3) ^ (row & 31)) << 4) | (((col >> 2) & 1) << 3))) = w;
	v_mfma_f32_16x16x32_bf16 v[94:97], v[188:191], v[236:239], v[94:97]
	ds_read_b128 v[228:231], v247 offset:8192
	v_mfma_f32_16x16x32_bf16 v[90:93], v[192:195], v[236:239], v[90:93]
	ds_read_b128 v[232:235], v247 offset:10240
	v_mfma_f32_16x16x32_bf16 v[86:89], v[220:223], v[236:239], v[86:89]
	v_mfma_f32_16x16x32_bf16 v[82:85], v[224:227], v[236:239], v[82:85]
	s_waitcnt lgkmcnt(2)
	v_mfma_f32_16x16x32_bf16 v[78:81], v[188:191], v[240:243], v[78:81]
	v_mfma_f32_16x16x32_bf16 v[74:77], v[192:195], v[240:243], v[74:77]
	v_mfma_f32_16x16x32_bf16 v[70:73], v[220:223], v[240:243], v[70:73]
	v_mfma_f32_16x16x32_bf16 v[66:69], v[224:227], v[240:243], v[66:69]
	s_waitcnt lgkmcnt(1)
	v_mfma_f32_16x16x32_bf16 v[62:65], v[188:191], v[228:231], v[62:65]
	ds_read_b128 v[236:239], v247 offset:12288
	v_mfma_f32_16x16x32_bf16 v[58:61], v[192:195], v[228:231], v[58:61]
	ds_read_b128 v[240:243], v247 offset:14336
	v_mfma_f32_16x16x32_bf16 v[54:57], v[220:223], v[228:231], v[54:57]
	v_mfma_f32_16x16x32_bf16 v[50:53], v[224:227], v[228:231], v[50:53]
	s_waitcnt lgkmcnt(2)
	v_mfma_f32_16x16x32_bf16 v[46:49], v[188:191], v[232:235], v[46:49]
	v_mfma_f32_16x16x32_bf16 v[42:45], v[192:195], v[232:235], v[42:45]
	v_mfma_f32_16x16x32_bf16 v[34:37], v[220:223], v[232:235], v[34:37]
	v_mfma_f32_16x16x32_bf16 v[30:33], v[224:227], v[232:235], v[30:33]
	s_waitcnt lgkmcnt(1)
	v_mfma_f32_16x16x32_bf16 v[26:29], v[188:191], v[236:239], v[26:29]
	v_mfma_f32_16x16x32_bf16 v[22:25], v[192:195], v[236:239], v[22:25]
	v_mfma_f32_16x16x32_bf16 v[18:21], v[220:223], v[236:239], v[18:21]
	v_mfma_f32_16x16x32_bf16 v[14:17], v[224:227], v[236:239], v[14:17]
	s_waitcnt lgkmcnt(0)
	v_mfma_f32_16x16x32_bf16 v[10:13], v[188:191], v[240:243], v[10:13]
	v_mfma_f32_16x16x32_bf16 v[6:9], v[192:195], v[240:243], v[6:9]
	v_mfma_f32_16x16x32_bf16 v[2:5], v[220:223], v[240:243], v[2:5]
	v_mfma_f32_16x16x32_bf16 v[38:41], v[224:227], v[240:243], v[38:41]
	s_cmp_eq_u32 s25, 0x1f0000
	s_cbranch_scc0 .LBB0_1003
	v_or_b32_e32 v172, 0x18000, v151
	v_add_u32_e32 v156, v172, v149
	s_waitcnt vmcnt(0)
	s_barrier
	ds_read_b128 v[138:141], v156
	ds_read_b128 v[152:155], v156 offset:2048
	ds_read_b128 v[176:179], v156 offset:4096
	ds_read_b128 v[180:183], v156 offset:6144
	v_add_u32_e32 v173, 0x10000, v148
	v_add_u32_e32 v188, v173, v149
	ds_read_b128 v[148:151], v188
	s_waitcnt lgkmcnt(0)
	v_mfma_f32_16x16x32_bf16 v[126:129], v[138:141], v[148:151], v[126:129]
	s_sext_i32_i8 s14, s24
	s_lshl_b32 s24, s14, 8
	s_lshl_b64 s[16:17], s[16:17], 21
	v_mfma_f32_16x16x32_bf16 v[122:125], v[152:155], v[148:151], v[122:125]
	s_ashr_i32 s25, s24, 31
	s_add_u32 s14, s4, s16
	s_addc_u32 s15, s5, s17
	v_mfma_f32_16x16x32_bf16 v[118:121], v[176:179], v[148:151], v[118:121]
	s_lshl_b64 s[16:17], s[24:25], 2
	v_lshl_add_u64 v[156:157], v[130:131], 0, s[18:19]
	s_add_u32 s16, s14, s16
	v_mfma_f32_16x16x32_bf16 v[114:117], v[180:183], v[148:151], v[114:117]
	ds_read_b128 v[148:151], v188 offset:2048
	s_addc_u32 s17, s15, s17
	s_mov_b32 s18, 0
	s_waitcnt lgkmcnt(0)
	v_mfma_f32_16x16x32_bf16 v[110:113], v[138:141], v[148:151], v[110:113]
	v_mfma_f32_16x16x32_bf16 v[106:109], v[152:155], v[148:151], v[106:109]
	v_mfma_f32_16x16x32_bf16 v[102:105], v[176:179], v[148:151], v[102:105]
	v_mfma_f32_16x16x32_bf16 v[98:101], v[180:183], v[148:151], v[98:101]
	ds_read_b128 v[148:151], v188 offset:4096
	s_waitcnt lgkmcnt(0)
	v_mfma_f32_16x16x32_bf16 v[94:97], v[138:141], v[148:151], v[94:97]
	v_mfma_f32_16x16x32_bf16 v[90:93], v[152:155], v[148:151], v[90:93]
	v_mfma_f32_16x16x32_bf16 v[86:89], v[176:179], v[148:151], v[86:89]
	v_mfma_f32_16x16x32_bf16 v[82:85], v[180:183], v[148:151], v[82:85]
	ds_read_b128 v[148:151], v188 offset:6144
	s_waitcnt lgkmcnt(0)
	v_mfma_f32_16x16x32_bf16 v[78:81], v[138:141], v[148:151], v[78:81]
	v_mfma_f32_16x16x32_bf16 v[74:77], v[152:155], v[148:151], v[74:77]
	v_mfma_f32_16x16x32_bf16 v[70:73], v[176:179], v[148:151], v[70:73]
	v_mfma_f32_16x16x32_bf16 v[66:69], v[180:183], v[148:151], v[66:69]
	ds_read_b128 v[148:151], v188 offset:8192
	ds_read_b128 v[184:187], v188 offset:10240
	s_waitcnt lgkmcnt(1)
	v_mfma_f32_16x16x32_bf16 v[62:65], v[138:141], v[148:151], v[62:65]
	v_mfma_f32_16x16x32_bf16 v[58:61], v[152:155], v[148:151], v[58:61]
	v_mfma_f32_16x16x32_bf16 v[54:57], v[176:179], v[148:151], v[54:57]
	v_mfma_f32_16x16x32_bf16 v[50:53], v[180:183], v[148:151], v[50:53]
	ds_read_b128 v[148:151], v188 offset:12288
	s_waitcnt lgkmcnt(1)
	v_mfma_f32_16x16x32_bf16 v[46:49], v[138:141], v[184:187], v[46:49]
	v_mfma_f32_16x16x32_bf16 v[42:45], v[152:155], v[184:187], v[42:45]
	v_mfma_f32_16x16x32_bf16 v[34:37], v[176:179], v[184:187], v[34:37]
	v_mfma_f32_16x16x32_bf16 v[30:33], v[180:183], v[184:187], v[30:33]
	ds_read_b128 v[184:187], v188 offset:14336
	s_waitcnt lgkmcnt(1)
	v_mfma_f32_16x16x32_bf16 v[188:191], v[138:141], v[148:151], v[26:29]
	s_nop 2
	v_add_u32_e32 v29, v172, v147
	ds_read_b128 v[192:195], v29
	ds_read_b128 v[196:199], v29 offset:2048
	ds_read_b128 v[200:203], v29 offset:4096
	ds_read_b128 v[204:207], v29 offset:6144
	v_add_u32_e32 v29, v173, v147
	v_mfma_f32_16x16x32_bf16 v[22:25], v[152:155], v[148:151], v[22:25]
	v_and_b32_e32 v28, 0xc0, v142
	v_lshl_or_b32 v145, v145, 2, v28
	v_lshlrev_b32_e32 v28, 3, v144
	v_mfma_f32_16x16x32_bf16 v[18:21], v[176:179], v[148:151], v[18:21]
	v_lshl_add_u64 v[26:27], s[24:25], 1, v[156:157]
	v_mfma_f32_16x16x32_bf16 v[14:17], v[180:183], v[148:151], v[14:17]
	ds_read_b128 v[148:151], v29
	ds_read_b128 v[208:211], v29 offset:2048
	ds_read_b128 v[212:215], v29 offset:4096
	ds_read_b128 v[216:219], v29 offset:6144
	s_waitcnt lgkmcnt(3)
	v_mfma_f32_16x16x32_bf16 v[126:129], v[192:195], v[148:151], v[126:129]
	v_mfma_f32_16x16x32_bf16 v[122:125], v[196:199], v[148:151], v[122:125]
	s_waitcnt lgkmcnt(1)
	v_mfma_f32_16x16x32_bf16 v[94:97], v[192:195], v[212:215], v[94:97]
	v_mfma_f32_16x16x32_bf16 v[10:13], v[138:141], v[184:187], v[10:13]
	ds_read_b128 v[138:141], v29 offset:8192
	ds_read_b128 v[220:223], v29 offset:10240
	ds_read_b128 v[224:227], v29 offset:12288
	ds_read_b128 v[228:231], v29 offset:14336
	v_lshlrev_b32_e32 v29, 9, v146
	v_and_or_b32 v144, v28, 8, v29
	v_mfma_f32_16x16x32_bf16 v[118:121], v[200:203], v[148:151], v[118:121]
	v_cvt_pk_bf16_f32 v28, v126, v127
	v_lshrrev_b32_e32 v126, 3, v145
	v_xor_b32_e32 v127, v126, v143
	v_mfma_f32_16x16x32_bf16 v[90:93], v[196:199], v[212:215], v[90:93]
	v_cvt_pk_bf16_f32 v29, v128, v129
	v_lshl_or_b32 v127, v127, 4, v144
	v_cvt_pk_bf16_f32 v122, v122, v123
	v_mfma_f32_16x16x32_bf16 v[114:117], v[204:207], v[148:151], v[114:117]
	v_cvt_pk_bf16_f32 v123, v124, v125
	v_bitop3_b32 v124, v126, v143, 2 bitop3:0x36
	v_cvt_pk_bf16_f32 v94, v94, v95
	v_mfma_f32_16x16x32_bf16 v[86:89], v[200:203], v[212:215], v[86:89]
	v_cvt_pk_bf16_f32 v95, v96, v97
	s_waitcnt lgkmcnt(0)
	s_barrier
; DEV unsigned cvt_pk_bf16(float lo, float hi) { const f32x2_t v = {lo, hi}; const bf16x2_t b = __builtin_convertvector(v, bf16x2_t); return __builtin_bit_cast(unsigned, b); }
; template <class Epi>
; DEV void gemm256_tile(const bf16_t* __restrict__ A, int lda, const bf16_t* __restrict__ Bt, int ldb, int K, unsigned char* lds, const Epi& epi) {
;     ...
;     if constexpr (Epi::STAGE) {
; #pragma unroll
;         for (int mi = 0; mi < 8; ++mi)
; #pragma unroll
;             for (int ni = 0; ni < 4; ++ni) {
;                 const int row = wr * 128 + mi * 16 + fr, col = wc * 64 + ni * 16 + fq * 4;
;                 const f32x4 v = epi.xform(row, col, acc[mi][ni]);
;                 uint2 w; w.x = cvt_pk_bf16(v[0], v[1]); w.y = cvt_pk_bf16(v[2], v[3]);
;                 *(uint2*)(lds + row * 512 + ((((col >> 3) ^ (row & 31)) << 4) | (((col >> 2) & 1) << 3))) = w;
;             }
;         __syncthreads();
	v_mfma_f32_16x16x32_bf16 v[110:113], v[192:195], v[208:211], v[110:113]
	v_lshl_add_u32 v124, v124, 4, v144
	v_cvt_pk_bf16_f32 v118, v118, v119
	v_mfma_f32_16x16x32_bf16 v[82:85], v[204:207], v[212:215], v[82:85]
	v_cvt_pk_bf16_f32 v119, v120, v121
	v_bitop3_b32 v120, v126, v143, 4 bitop3:0x36
	ds_write2st64_b64 v127, v[28:29], v[94:95] offset1:32
	v_mfma_f32_16x16x32_bf16 v[106:109], v[196:199], v[208:211], v[106:109]
	v_cvt_pk_bf16_f32 v28, v90, v91
	v_cvt_pk_bf16_f32 v29, v92, v93
	v_lshl_add_u32 v120, v120, 4, v144
	v_mfma_f32_16x16x32_bf16 v[78:81], v[192:195], v[216:219], v[78:81]
	v_cvt_pk_bf16_f32 v114, v114, v115
	v_cvt_pk_bf16_f32 v115, v116, v117
	v_bitop3_b32 v116, v126, v143, 6 bitop3:0x36
	v_mfma_f32_16x16x32_bf16 v[102:105], v[200:203], v[208:211], v[102:105]
	ds_write2st64_b64 v124, v[122:123], v[28:29] offset1:32
	v_cvt_pk_bf16_f32 v28, v86, v87
	v_cvt_pk_bf16_f32 v29, v88, v89
	v_mfma_f32_16x16x32_bf16 v[74:77], v[196:199], v[216:219], v[74:77]
	v_lshl_add_u32 v116, v116, 4, v144
	v_or_b32_e32 v117, 16, v143
	v_cvt_pk_bf16_f32 v110, v110, v111
	v_mfma_f32_16x16x32_bf16 v[2:5], v[176:179], v[184:187], v[2:5]
	v_cvt_pk_bf16_f32 v111, v112, v113
	v_bitop3_b32 v112, v126, v143, 16 bitop3:0x1e
	ds_write2st64_b64 v120, v[118:119], v[28:29] offset1:32
	v_mfma_f32_16x16x32_bf16 v[98:101], v[204:207], v[208:211], v[98:101]
	v_cvt_pk_bf16_f32 v28, v82, v83
	v_cvt_pk_bf16_f32 v29, v84, v85
	v_lshl_or_b32 v112, v112, 4, v144
	v_mfma_f32_16x16x32_bf16 v[70:73], v[200:203], v[216:219], v[70:73]
	v_cvt_pk_bf16_f32 v106, v106, v107
	v_cvt_pk_bf16_f32 v107, v108, v109
	v_bitop3_b32 v108, v126, v117, 2 bitop3:0x36
	v_mfma_f32_16x16x32_bf16 v[66:69], v[204:207], v[216:219], v[66:69]
	ds_write2st64_b64 v116, v[114:115], v[28:29] offset1:32
	v_cvt_pk_bf16_f32 v28, v78, v79
	v_cvt_pk_bf16_f32 v29, v80, v81
	v_lshl_add_u32 v108, v108, 4, v144
	v_cvt_pk_bf16_f32 v102, v102, v103
	v_cvt_pk_bf16_f32 v103, v104, v105
	v_bitop3_b32 v104, v126, v117, 4 bitop3:0x36
	ds_write2st64_b64 v112, v[110:111], v[28:29] offset0:16 offset1:48
	v_cvt_pk_bf16_f32 v28, v74, v75
	v_cvt_pk_bf16_f32 v29, v76, v77
	v_lshl_add_u32 v104, v104, 4, v144
	v_cvt_pk_bf16_f32 v98, v98, v99
	v_cvt_pk_bf16_f32 v99, v100, v101
	v_bitop3_b32 v100, v126, v117, 6 bitop3:0x36
	ds_write2st64_b64 v108, v[106:107], v[28:29] offset0:16 offset1:48
	v_cvt_pk_bf16_f32 v28, v70, v71
	v_cvt_pk_bf16_f32 v29, v72, v73
	v_mfma_f32_16x16x32_bf16 v[34:37], v[200:203], v[220:223], v[34:37]
	v_lshl_add_u32 v100, v100, 4, v144
	ds_write2st64_b64 v104, v[102:103], v[28:29] offset0:16 offset1:48
	v_cvt_pk_bf16_f32 v28, v66, v67
	v_mfma_f32_16x16x32_bf16 v[2:5], v[200:203], v[228:231], v[2:5]
	v_cvt_pk_bf16_f32 v29, v68, v69
	ds_write2st64_b64 v100, v[98:99], v[28:29] offset0:16 offset1:48
	s_nop 1
	v_cvt_pk_bf16_f32 v34, v34, v35
	v_mfma_f32_16x16x32_bf16 v[38:41], v[180:183], v[184:187], v[38:41]
	v_cvt_pk_bf16_f32 v35, v36, v37
	s_nop 0
	v_cvt_pk_bf16_f32 v2, v2, v3
	v_cvt_pk_bf16_f32 v3, v4, v5
	v_mfma_f32_16x16x32_bf16 v[6:9], v[152:155], v[184:187], v[6:9]
	ds_write2st64_b64 v104, v[34:35], v[2:3] offset0:80 offset1:112
	v_mfma_f32_16x16x32_bf16 v[28:31], v[204:207], v[220:223], v[30:33]
	v_mfma_f32_16x16x32_bf16 v[2:5], v[204:207], v[228:231], v[38:41]
	v_mfma_f32_16x16x32_bf16 v[62:65], v[192:195], v[138:141], v[62:65]
	s_nop 5
	v_cvt_pk_bf16_f32 v32, v28, v29
	v_cvt_pk_bf16_f32 v33, v30, v31
	v_cvt_pk_bf16_f32 v2, v2, v3
	v_mfma_f32_16x16x32_bf16 v[58:61], v[196:199], v[138:141], v[58:61]
	v_cvt_pk_bf16_f32 v3, v4, v5
	v_cvt_pk_bf16_f32 v62, v62, v63
	v_cvt_pk_bf16_f32 v63, v64, v65
	v_mfma_f32_16x16x32_bf16 v[54:57], v[200:203], v[138:141], v[54:57]
	ds_write2st64_b64 v100, v[32:33], v[2:3] offset0:80 offset1:112
	s_nop 2
	v_cvt_pk_bf16_f32 v58, v58, v59
	v_cvt_pk_bf16_f32 v59, v60, v61
	v_mfma_f32_16x16x32_bf16 v[50:53], v[204:207], v[138:141], v[50:53]
	v_and_b32_e32 v2, 0x1f0, v136
	v_cvt_pk_bf16_f32 v54, v54, v55
	v_cvt_pk_bf16_f32 v55, v56, v57
	v_mfma_f32_16x16x32_bf16 v[46:49], v[192:195], v[220:223], v[46:49]
	v_mfma_f32_16x16x32_bf16 v[42:45], v[196:199], v[220:223], v[42:45]
	s_nop 2
	v_cvt_pk_bf16_f32 v50, v50, v51
	v_cvt_pk_bf16_f32 v51, v52, v53
	s_nop 1
	v_cvt_pk_bf16_f32 v46, v46, v47
	v_mfma_f32_16x16x32_bf16 v[28:31], v[192:195], v[224:227], v[188:191]
	v_cvt_pk_bf16_f32 v47, v48, v49
	v_cvt_pk_bf16_f32 v42, v42, v43
	v_cvt_pk_bf16_f32 v43, v44, v45
	v_mfma_f32_16x16x32_bf16 v[22:25], v[196:199], v[224:227], v[22:25]
	v_mfma_f32_16x16x32_bf16 v[18:21], v[200:203], v[224:227], v[18:21]
	s_nop 2
	v_cvt_pk_bf16_f32 v28, v28, v29
	v_cvt_pk_bf16_f32 v29, v30, v31
	s_nop 1
	v_cvt_pk_bf16_f32 v22, v22, v23
	v_mfma_f32_16x16x32_bf16 v[14:17], v[204:207], v[224:227], v[14:17]
	v_cvt_pk_bf16_f32 v23, v24, v25
	v_cvt_pk_bf16_f32 v18, v18, v19
	v_cvt_pk_bf16_f32 v19, v20, v21
	v_mfma_f32_16x16x32_bf16 v[10:13], v[192:195], v[228:231], v[10:13]
	ds_write2st64_b64 v127, v[62:63], v[28:29] offset0:64 offset1:96
	s_nop 2
	v_cvt_pk_bf16_f32 v14, v14, v15
	v_cvt_pk_bf16_f32 v15, v16, v17
	v_mfma_f32_16x16x32_bf16 v[6:9], v[196:199], v[228:231], v[6:9]
	ds_write2st64_b64 v124, v[58:59], v[22:23] offset0:64 offset1:96
	v_cvt_pk_bf16_f32 v10, v10, v11
	v_cvt_pk_bf16_f32 v11, v12, v13
	ds_write2st64_b64 v120, v[54:55], v[18:19] offset0:64 offset1:96
	ds_write2st64_b64 v116, v[50:51], v[14:15] offset0:64 offset1:96
	s_nop 2
	v_cvt_pk_bf16_f32 v6, v6, v7
	v_cvt_pk_bf16_f32 v7, v8, v9
	ds_write2st64_b64 v112, v[46:47], v[10:11] offset0:80 offset1:112
	ds_write2st64_b64 v108, v[42:43], v[6:7] offset0:80 offset1:112
	s_waitcnt lgkmcnt(0)
	s_barrier

; #define GLDS_STAGE(st, kt_) do { \
;         _Pragma("unroll") for (int i_ = 0; i_ < FI; ++i_) { \
;             glds16(ap + (size_t)(32 * i_) * lda + (kt_) * 64, l3a + (st) + tid * 16 + i_ * 4096); \
;             glds16(bp + (size_t)(32 * i_) * ldb + (kt_) * 64, l3a + (st) + OPB + tid * 16 + i_ * 4096); } } while (0)
; #define GLDS_STAGE(st, kt_) do { \
;         _Pragma("unroll") for (int i_ = 0; i_ < 4; ++i_) { \
;             glds16(ap + (size_t)(64 * i_) * lda + (kt_) * 64, l3a + (st) + tid * 16 + i_ * 8192); \
;             glds16(bp + (size_t)(64 * i_) * ldb + (kt_) * 64, l3a + (st) + 32768 + tid * 16 + i_ * 8192); } } while (0)
; template <class Epi>
; DEV void gemm256_tile(const bf16_t* __restrict__ A, int lda, const bf16_t* __restrict__ Bt, int ldb, int K, unsigned char* lds, const Epi& epi) {
;     ...
;     for (int kt = 0; kt < nk; ++kt) {
;         const int cur = (kt & 1) * 65536;
;         asm volatile("s_waitcnt vmcnt(0)" ::: "memory");
;         __syncthreads();
;         if (kt + 1 < nk) GLDS_STAGE(cur ^ 65536, kt + 1);
; #pragma unroll
;         for (int kh = 0; kh < 2; ++kh) {
;             bf16x8 bfr[4];
;             const int ch = ((kh * 4 + fq) ^ sw) << 4;
; #pragma unroll
;             for (int i = 0; i < 4; ++i) bfr[i] = *(const bf16x8*)(lds + cur + boff + i * 2048 + ch);
; #pragma unroll
;             for (int mh = 0; mh < 2; ++mh) {
;                 bf16x8 af[4];
; #pragma unroll
;                 for (int i = 0; i < 4; ++i) af[i] = *(const bf16x8*)(lds + cur + aoff + (mh * 4 + i) * 2048 + ch);
; #pragma unroll
;                 for (int mi = 0; mi < 4; ++mi)
; #pragma unroll
;                     for (int ni = 0; ni < 4; ++ni) acc[mh * 4 + mi][ni] = __builtin_amdgcn_mfma_f32_16x16x32_bf16(bfr[ni], af[mi], acc[mh * 4 + mi][ni], 0, 0, 0);
;             }
;         }
;     }
.LBB0_1236:
	s_and_b32 s48, s21, 0x10000
	s_xor_b32 s49, s48, 0x10000
	v_add_u32_e32 v216, s49, v138
	v_add_u32_e32 v217, s49, v150
	s_waitcnt vmcnt(0) lgkmcnt(0)
	s_barrier
	v_or_b32_e32 v248, s48, v153
	v_add_u32_e32 v249, s48, v151
	v_add_u32_e32 v244, v248, v152
	v_add_u32_e32 v245, v249, v152
	ds_read_b128 v[154:157], v244 offset:32768
	ds_read_b128 v[228:231], v245
	ds_read_b128 v[170:173], v244 offset:34816
	ds_read_b128 v[174:177], v244 offset:36864
	ds_read_b128 v[178:181], v244 offset:38912
	ds_read_b128 v[232:235], v245 offset:2048
	ds_read_b128 v[236:239], v245 offset:4096
	ds_read_b128 v[240:243], v245 offset:6144
	v_readfirstlane_b32 s40, v216
	v_readfirstlane_b32 s44, v217
	v_add_u32_e32 v246, v248, v149
	v_add_u32_e32 v247, v249, v149
	s_mov_b32 m0, s40
	v_lshl_add_u64 v[204:205], v[140:141], 0, s[4:5]
	global_load_lds_dwordx4 v[140:141], off
	s_mov_b32 m0, s44
	v_lshl_add_u64 v[210:211], v[142:143], 0, s[4:5]
	global_load_lds_dwordx4 v[142:143], off
	s_add_i32 s41, s40, 0x2000
	s_add_i32 s45, s44, 0x2000
	s_add_i32 s42, s40, 0x4000
	s_add_i32 s46, s44, 0x4000
	s_add_i32 s43, s40, 0x6000
	s_add_i32 s47, s44, 0x6000
	s_add_i32 s21, s21, 0x10000
	s_waitcnt lgkmcnt(6)
	v_mfma_f32_16x16x32_bf16 v[126:129], v[154:157], v[228:231], v[126:129]
	v_lshl_add_u64 v[206:207], v[140:141], 0, s[6:7]
	s_waitcnt lgkmcnt(5)
	v_mfma_f32_16x16x32_bf16 v[122:125], v[170:173], v[228:231], v[122:125]
	v_lshl_add_u64 v[212:213], v[142:143], 0, s[6:7]
	s_waitcnt lgkmcnt(4)
	v_mfma_f32_16x16x32_bf16 v[118:121], v[174:177], v[228:231], v[118:121]
	v_lshl_add_u64 v[208:209], v[140:141], 0, s[8:9]
	s_waitcnt lgkmcnt(3)
	v_mfma_f32_16x16x32_bf16 v[114:117], v[178:181], v[228:231], v[114:117]
	v_lshl_add_u64 v[214:215], v[142:143], 0, s[8:9]
	s_waitcnt lgkmcnt(2)
	v_mfma_f32_16x16x32_bf16 v[110:113], v[154:157], v[232:235], v[110:113]
	v_mfma_f32_16x16x32_bf16 v[106:109], v[170:173], v[232:235], v[106:109]
	v_mfma_f32_16x16x32_bf16 v[102:105], v[174:177], v[232:235], v[102:105]
	v_mfma_f32_16x16x32_bf16 v[98:101], v[178:181], v[232:235], v[98:101]
	s_waitcnt lgkmcnt(1)
	v_mfma_f32_16x16x32_bf16 v[94:97], v[154:157], v[236:239], v[94:97]
	ds_read_b128 v[228:231], v245 offset:8192
	v_mfma_f32_16x16x32_bf16 v[90:93], v[170:173], v[236:239], v[90:93]
	ds_read_b128 v[232:235], v245 offset:10240
	v_mfma_f32_16x16x32_bf16 v[86:89], v[174:177], v[236:239], v[86:89]
	s_mov_b32 m0, s41
	v_mfma_f32_16x16x32_bf16 v[82:85], v[178:181], v[236:239], v[82:85]
	global_load_lds_dwordx4 v[204:205], off
	s_waitcnt lgkmcnt(2)
	v_mfma_f32_16x16x32_bf16 v[78:81], v[154:157], v[240:243], v[78:81]
	s_mov_b32 m0, s45
	v_mfma_f32_16x16x32_bf16 v[74:77], v[170:173], v[240:243], v[74:77]
	global_load_lds_dwordx4 v[210:211], off
	v_mfma_f32_16x16x32_bf16 v[70:73], v[174:177], v[240:243], v[70:73]
	v_mfma_f32_16x16x32_bf16 v[66:69], v[178:181], v[240:243], v[66:69]
	s_waitcnt lgkmcnt(1)
	v_mfma_f32_16x16x32_bf16 v[62:65], v[154:157], v[228:231], v[62:65]
	ds_read_b128 v[236:239], v245 offset:12288
	v_mfma_f32_16x16x32_bf16 v[58:61], v[170:173], v[228:231], v[58:61]
	ds_read_b128 v[240:243], v245 offset:14336
	v_mfma_f32_16x16x32_bf16 v[54:57], v[174:177], v[228:231], v[54:57]
	s_mov_b32 m0, s42
	v_mfma_f32_16x16x32_bf16 v[50:53], v[178:181], v[228:231], v[50:53]
	global_load_lds_dwordx4 v[206:207], off
	s_waitcnt lgkmcnt(2)
	v_mfma_f32_16x16x32_bf16 v[46:49], v[154:157], v[232:235], v[46:49]
	s_mov_b32 m0, s46
	v_mfma_f32_16x16x32_bf16 v[42:45], v[170:173], v[232:235], v[42:45]
	global_load_lds_dwordx4 v[212:213], off
	v_mfma_f32_16x16x32_bf16 v[34:37], v[174:177], v[232:235], v[34:37]
	v_mfma_f32_16x16x32_bf16 v[30:33], v[178:181], v[232:235], v[30:33]
	s_waitcnt lgkmcnt(1)
	v_mfma_f32_16x16x32_bf16 v[26:29], v[154:157], v[236:239], v[26:29]
	ds_read_b128 v[182:185], v246 offset:32768
	v_mfma_f32_16x16x32_bf16 v[22:25], v[170:173], v[236:239], v[22:25]
	ds_read_b128 v[186:189], v246 offset:34816
	v_mfma_f32_16x16x32_bf16 v[18:21], v[174:177], v[236:239], v[18:21]
	ds_read_b128 v[220:223], v246 offset:36864
	v_mfma_f32_16x16x32_bf16 v[14:17], v[178:181], v[236:239], v[14:17]
	ds_read_b128 v[224:227], v246 offset:38912
	s_waitcnt lgkmcnt(4)
	v_mfma_f32_16x16x32_bf16 v[10:13], v[154:157], v[240:243], v[10:13]
	ds_read_b128 v[228:231], v247
	v_mfma_f32_16x16x32_bf16 v[6:9], v[170:173], v[240:243], v[6:9]
	ds_read_b128 v[232:235], v247 offset:2048
	v_mfma_f32_16x16x32_bf16 v[2:5], v[174:177], v[240:243], v[2:5]
	s_mov_b32 m0, s43
	v_mfma_f32_16x16x32_bf16 v[38:41], v[178:181], v[240:243], v[38:41]
	global_load_lds_dwordx4 v[208:209], off
	s_mov_b32 m0, s47
	v_lshl_add_u64 v[140:141], v[140:141], 0, s[10:11]
	global_load_lds_dwordx4 v[214:215], off
	v_lshl_add_u64 v[142:143], v[142:143], 0, s[10:11]
	s_waitcnt lgkmcnt(1)
	v_mfma_f32_16x16x32_bf16 v[126:129], v[182:185], v[228:231], v[126:129]
	ds_read_b128 v[236:239], v247 offset:4096
	v_mfma_f32_16x16x32_bf16 v[122:125], v[186:189], v[228:231], v[122:125]
	ds_read_b128 v[240:243], v247 offset:6144
	v_mfma_f32_16x16x32_bf16 v[118:121], v[220:223], v[228:231], v[118:121]
	v_mfma_f32_16x16x32_bf16 v[114:117], v[224:227], v[228:231], v[114:117]
	s_waitcnt lgkmcnt(2)
	v_mfma_f32_16x16x32_bf16 v[110:113], v[182:185], v[232:235], v[110:113]
	v_mfma_f32_16x16x32_bf16 v[106:109], v[186:189], v[232:235], v[106:109]
	v_mfma_f32_16x16x32_bf16 v[102:105], v[220:223], v[232:235], v[102:105]
	v_mfma_f32_16x16x32_bf16 v[98:101], v[224:227], v[232:235], v[98:101]
	s_waitcnt lgkmcnt(1)
; DEV unsigned cvt_pk_bf16(float lo, float hi) { const f32x2_t v = {lo, hi}; const bf16x2_t b = __builtin_convertvector(v, bf16x2_t); return __builtin_bit_cast(unsigned, b); }
; #define GLDS_STAGE(st, kt_) do { \
;         _Pragma("unroll") for (int i_ = 0; i_ < FI; ++i_) { \
;             glds16(ap + (size_t)(32 * i_) * lda + (kt_) * 64, l3a + (st) + tid * 16 + i_ * 4096); \
;             glds16(bp + (size_t)(32 * i_) * ldb + (kt_) * 64, l3a + (st) + OPB + tid * 16 + i_ * 4096); } } while (0)
; template <class Epi>
; DEV void gemm256_tile(const bf16_t* __restrict__ A, int lda, const bf16_t* __restrict__ Bt, int ldb, int K, unsigned char* lds, const Epi& epi) {
;     ...
;     for (int kt = 0; kt < nk; ++kt) {
;         const int cur = (kt & 1) * 65536;
;         asm volatile("s_waitcnt vmcnt(0)" ::: "memory");
;         __syncthreads();
;         if (kt + 1 < nk) GLDS_STAGE(cur ^ 65536, kt + 1);
; #pragma unroll
;         for (int kh = 0; kh < 2; ++kh) {
;             bf16x8 bfr[4];
;             const int ch = ((kh * 4 + fq) ^ sw) << 4;
; #pragma unroll
;             for (int i = 0; i < 4; ++i) bfr[i] = *(const bf16x8*)(lds + cur + boff + i * 2048 + ch);
; #pragma unroll
;             for (int mh = 0; mh < 2; ++mh) {
;                 bf16x8 af[4];
; #pragma unroll
;                 for (int i = 0; i < 4; ++i) af[i] = *(const bf16x8*)(lds + cur + aoff + (mh * 4 + i) * 2048 + ch);
; #pragma unroll
;                 for (int mi = 0; mi < 4; ++mi)
; #pragma unroll
;                     for (int ni = 0; ni < 4; ++ni) acc[mh * 4 + mi][ni] = __builtin_amdgcn_mfma_f32_16x16x32_bf16(bfr[ni], af[mi], acc[mh * 4 + mi][ni], 0, 0, 0);
;             }
;         }
;     }
;     ...
;     __syncthreads();
;     if constexpr (Epi::STAGE) {
; #pragma unroll
;         for (int mi = 0; mi < 8; ++mi)
; #pragma unroll
;             for (int ni = 0; ni < 4; ++ni) {
;                 const int row = wr * 128 + mi * 16 + fr, col = wc * 64 + ni * 16 + fq * 4;
;                 const f32x4 v = epi.xform(row, col, acc[mi][ni]);
;                 uint2 w; w.x = cvt_pk_bf16(v[0], v[1]); w.y = cvt_pk_bf16(v[2], v[3]);
;                 *(uint2*)(lds + row * 512 + ((((col >> 3) ^ (row & 31)) << 4) | (((col >> 2) & 1) << 3))) = w;
	v_mfma_f32_16x16x32_bf16 v[94:97], v[182:185], v[236:239], v[94:97]
	ds_read_b128 v[228:231], v247 offset:8192
	v_mfma_f32_16x16x32_bf16 v[90:93], v[186:189], v[236:239], v[90:93]
	ds_read_b128 v[232:235], v247 offset:10240
	v_mfma_f32_16x16x32_bf16 v[86:89], v[220:223], v[236:239], v[86:89]
	v_mfma_f32_16x16x32_bf16 v[82:85], v[224:227], v[236:239], v[82:85]
	s_waitcnt lgkmcnt(2)
	v_mfma_f32_16x16x32_bf16 v[78:81], v[182:185], v[240:243], v[78:81]
	v_mfma_f32_16x16x32_bf16 v[74:77], v[186:189], v[240:243], v[74:77]
	v_mfma_f32_16x16x32_bf16 v[70:73], v[220:223], v[240:243], v[70:73]
	v_mfma_f32_16x16x32_bf16 v[66:69], v[224:227], v[240:243], v[66:69]
	s_waitcnt lgkmcnt(1)
	v_mfma_f32_16x16x32_bf16 v[62:65], v[182:185], v[228:231], v[62:65]
	ds_read_b128 v[236:239], v247 offset:12288
	v_mfma_f32_16x16x32_bf16 v[58:61], v[186:189], v[228:231], v[58:61]
	ds_read_b128 v[240:243], v247 offset:14336
	v_mfma_f32_16x16x32_bf16 v[54:57], v[220:223], v[228:231], v[54:57]
	v_mfma_f32_16x16x32_bf16 v[50:53], v[224:227], v[228:231], v[50:53]
	s_waitcnt lgkmcnt(2)
	v_mfma_f32_16x16x32_bf16 v[46:49], v[182:185], v[232:235], v[46:49]
	v_mfma_f32_16x16x32_bf16 v[42:45], v[186:189], v[232:235], v[42:45]
	v_mfma_f32_16x16x32_bf16 v[34:37], v[220:223], v[232:235], v[34:37]
	v_mfma_f32_16x16x32_bf16 v[30:33], v[224:227], v[232:235], v[30:33]
	s_waitcnt lgkmcnt(1)
	v_mfma_f32_16x16x32_bf16 v[26:29], v[182:185], v[236:239], v[26:29]
	v_mfma_f32_16x16x32_bf16 v[22:25], v[186:189], v[236:239], v[22:25]
	v_mfma_f32_16x16x32_bf16 v[18:21], v[220:223], v[236:239], v[18:21]
	v_mfma_f32_16x16x32_bf16 v[14:17], v[224:227], v[236:239], v[14:17]
	s_waitcnt lgkmcnt(0)
	v_mfma_f32_16x16x32_bf16 v[10:13], v[182:185], v[240:243], v[10:13]
	v_mfma_f32_16x16x32_bf16 v[6:9], v[186:189], v[240:243], v[6:9]
	v_mfma_f32_16x16x32_bf16 v[2:5], v[220:223], v[240:243], v[2:5]
	v_mfma_f32_16x16x32_bf16 v[38:41], v[224:227], v[240:243], v[38:41]
	s_cmp_eq_u32 s21, 0x1f0000
	s_cbranch_scc0 .LBB0_1236
	v_or_b32_e32 v186, 0x18000, v153
	v_add_u32_e32 v202, 0x10000, v151
	v_add_u32_e32 v174, v186, v152
	v_add_u32_e32 v182, v202, v152
	s_waitcnt vmcnt(0)
	s_barrier
	ds_read_b128 v[140:143], v174
	ds_read_b128 v[154:157], v174 offset:2048
	ds_read_b128 v[150:153], v182
	ds_read_b128 v[170:173], v174 offset:4096
	ds_read_b128 v[174:177], v174 offset:6144
	s_waitcnt lgkmcnt(2)
	v_mfma_f32_16x16x32_bf16 v[126:129], v[140:143], v[150:153], v[126:129]
	s_sext_i32_i8 s14, s20
	s_lshl_b32 s20, s14, 8
	s_ashr_i32 s21, s20, 31
	v_mfma_f32_16x16x32_bf16 v[122:125], v[154:157], v[150:153], v[122:125]
	s_waitcnt lgkmcnt(1)
	v_mfma_f32_16x16x32_bf16 v[118:121], v[170:173], v[150:153], v[118:121]
	s_waitcnt lgkmcnt(0)
	v_mfma_f32_16x16x32_bf16 v[114:117], v[174:177], v[150:153], v[114:117]
	ds_read_b128 v[150:153], v182 offset:2048
	s_waitcnt lgkmcnt(0)
	v_mfma_f32_16x16x32_bf16 v[110:113], v[140:143], v[150:153], v[110:113]
	v_mfma_f32_16x16x32_bf16 v[106:109], v[154:157], v[150:153], v[106:109]
	v_mfma_f32_16x16x32_bf16 v[102:105], v[170:173], v[150:153], v[102:105]
	v_mfma_f32_16x16x32_bf16 v[98:101], v[174:177], v[150:153], v[98:101]
	ds_read_b128 v[150:153], v182 offset:4096
	s_waitcnt lgkmcnt(0)
	v_mfma_f32_16x16x32_bf16 v[94:97], v[140:143], v[150:153], v[94:97]
	v_mfma_f32_16x16x32_bf16 v[90:93], v[154:157], v[150:153], v[90:93]
	v_mfma_f32_16x16x32_bf16 v[86:89], v[170:173], v[150:153], v[86:89]
	v_mfma_f32_16x16x32_bf16 v[82:85], v[174:177], v[150:153], v[82:85]
	ds_read_b128 v[150:153], v182 offset:6144
	s_waitcnt lgkmcnt(0)
	v_mfma_f32_16x16x32_bf16 v[78:81], v[140:143], v[150:153], v[78:81]
	v_mfma_f32_16x16x32_bf16 v[74:77], v[154:157], v[150:153], v[74:77]
	v_mfma_f32_16x16x32_bf16 v[70:73], v[170:173], v[150:153], v[70:73]
	v_mfma_f32_16x16x32_bf16 v[66:69], v[174:177], v[150:153], v[66:69]
	ds_read_b128 v[150:153], v182 offset:8192
	ds_read_b128 v[178:181], v182 offset:10240
	s_waitcnt lgkmcnt(1)
	v_mfma_f32_16x16x32_bf16 v[62:65], v[140:143], v[150:153], v[62:65]
	v_mfma_f32_16x16x32_bf16 v[58:61], v[154:157], v[150:153], v[58:61]
	v_mfma_f32_16x16x32_bf16 v[54:57], v[170:173], v[150:153], v[54:57]
	v_mfma_f32_16x16x32_bf16 v[50:53], v[174:177], v[150:153], v[50:53]
	ds_read_b128 v[150:153], v182 offset:12288
	s_waitcnt lgkmcnt(1)
	v_mfma_f32_16x16x32_bf16 v[46:49], v[140:143], v[178:181], v[46:49]
	v_mfma_f32_16x16x32_bf16 v[42:45], v[154:157], v[178:181], v[42:45]
	v_mfma_f32_16x16x32_bf16 v[34:37], v[170:173], v[178:181], v[34:37]
	v_mfma_f32_16x16x32_bf16 v[30:33], v[174:177], v[178:181], v[30:33]
	ds_read_b128 v[178:181], v182 offset:14336
	s_waitcnt lgkmcnt(1)
	v_mfma_f32_16x16x32_bf16 v[182:185], v[140:143], v[150:153], v[26:29]
	s_nop 2
	v_add_u32_e32 v29, v186, v149
	ds_read_b128 v[186:189], v29
	ds_read_b128 v[190:193], v29 offset:2048
	ds_read_b128 v[194:197], v29 offset:4096
	ds_read_b128 v[198:201], v29 offset:6144
	v_add_u32_e32 v29, v202, v149
	v_mfma_f32_16x16x32_bf16 v[22:25], v[154:157], v[150:153], v[22:25]
	v_and_b32_e32 v28, 0xc0, v144
	v_lshl_or_b32 v147, v147, 2, v28
	v_lshlrev_b32_e32 v28, 3, v146
	v_mfma_f32_16x16x32_bf16 v[18:21], v[170:173], v[150:153], v[18:21]
	v_lshl_add_u64 v[26:27], v[132:133], 0, s[12:13]
	v_lshl_add_u64 v[26:27], s[20:21], 1, v[26:27]
	s_mov_b32 s12, 0
	v_mfma_f32_16x16x32_bf16 v[14:17], v[174:177], v[150:153], v[14:17]
	ds_read_b128 v[150:153], v29
	ds_read_b128 v[202:205], v29 offset:2048
	ds_read_b128 v[206:209], v29 offset:4096
	ds_read_b128 v[210:213], v29 offset:6144
	s_waitcnt lgkmcnt(3)
	v_mfma_f32_16x16x32_bf16 v[126:129], v[186:189], v[150:153], v[126:129]
	v_mfma_f32_16x16x32_bf16 v[122:125], v[190:193], v[150:153], v[122:125]
	s_waitcnt lgkmcnt(1)
	v_mfma_f32_16x16x32_bf16 v[94:97], v[186:189], v[206:209], v[94:97]
	v_mfma_f32_16x16x32_bf16 v[10:13], v[140:143], v[178:181], v[10:13]
	ds_read_b128 v[140:143], v29 offset:8192
	ds_read_b128 v[214:217], v29 offset:10240
	ds_read_b128 v[218:221], v29 offset:12288
	ds_read_b128 v[222:225], v29 offset:14336
	v_lshlrev_b32_e32 v29, 9, v148
	v_and_or_b32 v146, v28, 8, v29
	v_mfma_f32_16x16x32_bf16 v[118:121], v[194:197], v[150:153], v[118:121]
	v_cvt_pk_bf16_f32 v28, v126, v127
	v_lshrrev_b32_e32 v126, 3, v147
	v_xor_b32_e32 v127, v126, v145
	v_mfma_f32_16x16x32_bf16 v[90:93], v[190:193], v[206:209], v[90:93]
	v_cvt_pk_bf16_f32 v29, v128, v129
	v_lshl_or_b32 v127, v127, 4, v146
	v_cvt_pk_bf16_f32 v122, v122, v123
	v_mfma_f32_16x16x32_bf16 v[114:117], v[198:201], v[150:153], v[114:117]
	v_cvt_pk_bf16_f32 v123, v124, v125
	v_bitop3_b32 v124, v126, v145, 2 bitop3:0x36
	v_cvt_pk_bf16_f32 v94, v94, v95
	v_mfma_f32_16x16x32_bf16 v[86:89], v[194:197], v[206:209], v[86:89]
	v_cvt_pk_bf16_f32 v95, v96, v97
	s_waitcnt lgkmcnt(0)
	s_barrier
; DEV unsigned cvt_pk_bf16(float lo, float hi) { const f32x2_t v = {lo, hi}; const bf16x2_t b = __builtin_convertvector(v, bf16x2_t); return __builtin_bit_cast(unsigned, b); }
; template <class Epi>
; DEV void gemm256_tile(const bf16_t* __restrict__ A, int lda, const bf16_t* __restrict__ Bt, int ldb, int K, unsigned char* lds, const Epi& epi) {
;     ...
;     if constexpr (Epi::STAGE) {
; #pragma unroll
;         for (int mi = 0; mi < 8; ++mi)
; #pragma unroll
;             for (int ni = 0; ni < 4; ++ni) {
;                 const int row = wr * 128 + mi * 16 + fr, col = wc * 64 + ni * 16 + fq * 4;
;                 const f32x4 v = epi.xform(row, col, acc[mi][ni]);
;                 uint2 w; w.x = cvt_pk_bf16(v[0], v[1]); w.y = cvt_pk_bf16(v[2], v[3]);
;                 *(uint2*)(lds + row * 512 + ((((col >> 3) ^ (row & 31)) << 4) | (((col >> 2) & 1) << 3))) = w;
;             }
;         __syncthreads();
	v_mfma_f32_16x16x32_bf16 v[110:113], v[186:189], v[202:205], v[110:113]
	v_lshl_add_u32 v124, v124, 4, v146
	v_cvt_pk_bf16_f32 v118, v118, v119
	v_mfma_f32_16x16x32_bf16 v[82:85], v[198:201], v[206:209], v[82:85]
	v_cvt_pk_bf16_f32 v119, v120, v121
	v_bitop3_b32 v120, v126, v145, 4 bitop3:0x36
	ds_write2st64_b64 v127, v[28:29], v[94:95] offset1:32
	v_mfma_f32_16x16x32_bf16 v[106:109], v[190:193], v[202:205], v[106:109]
	v_cvt_pk_bf16_f32 v28, v90, v91
	v_cvt_pk_bf16_f32 v29, v92, v93
	v_lshl_add_u32 v120, v120, 4, v146
	v_mfma_f32_16x16x32_bf16 v[78:81], v[186:189], v[210:213], v[78:81]
	v_cvt_pk_bf16_f32 v114, v114, v115
	v_cvt_pk_bf16_f32 v115, v116, v117
	v_bitop3_b32 v116, v126, v145, 6 bitop3:0x36
	v_mfma_f32_16x16x32_bf16 v[102:105], v[194:197], v[202:205], v[102:105]
	ds_write2st64_b64 v124, v[122:123], v[28:29] offset1:32
	v_cvt_pk_bf16_f32 v28, v86, v87
	v_cvt_pk_bf16_f32 v29, v88, v89
	v_mfma_f32_16x16x32_bf16 v[74:77], v[190:193], v[210:213], v[74:77]
	v_lshl_add_u32 v116, v116, 4, v146
	v_or_b32_e32 v117, 16, v145
	v_cvt_pk_bf16_f32 v110, v110, v111
	v_mfma_f32_16x16x32_bf16 v[2:5], v[170:173], v[178:181], v[2:5]
	v_cvt_pk_bf16_f32 v111, v112, v113
	v_bitop3_b32 v112, v126, v145, 16 bitop3:0x1e
	ds_write2st64_b64 v120, v[118:119], v[28:29] offset1:32
	v_mfma_f32_16x16x32_bf16 v[98:101], v[198:201], v[202:205], v[98:101]
	v_cvt_pk_bf16_f32 v28, v82, v83
	v_cvt_pk_bf16_f32 v29, v84, v85
	v_lshl_or_b32 v112, v112, 4, v146
	v_mfma_f32_16x16x32_bf16 v[70:73], v[194:197], v[210:213], v[70:73]
	v_cvt_pk_bf16_f32 v106, v106, v107
	v_cvt_pk_bf16_f32 v107, v108, v109
	v_bitop3_b32 v108, v126, v117, 2 bitop3:0x36
	v_mfma_f32_16x16x32_bf16 v[66:69], v[198:201], v[210:213], v[66:69]
	ds_write2st64_b64 v116, v[114:115], v[28:29] offset1:32
	v_cvt_pk_bf16_f32 v28, v78, v79
	v_cvt_pk_bf16_f32 v29, v80, v81
	v_lshl_add_u32 v108, v108, 4, v146
	v_cvt_pk_bf16_f32 v102, v102, v103
	v_cvt_pk_bf16_f32 v103, v104, v105
	v_bitop3_b32 v104, v126, v117, 4 bitop3:0x36
	ds_write2st64_b64 v112, v[110:111], v[28:29] offset0:16 offset1:48
	v_cvt_pk_bf16_f32 v28, v74, v75
	v_cvt_pk_bf16_f32 v29, v76, v77
	v_lshl_add_u32 v104, v104, 4, v146
	v_cvt_pk_bf16_f32 v98, v98, v99
	v_cvt_pk_bf16_f32 v99, v100, v101
	v_bitop3_b32 v100, v126, v117, 6 bitop3:0x36
	ds_write2st64_b64 v108, v[106:107], v[28:29] offset0:16 offset1:48
	v_cvt_pk_bf16_f32 v28, v70, v71
	v_cvt_pk_bf16_f32 v29, v72, v73
	v_mfma_f32_16x16x32_bf16 v[34:37], v[194:197], v[214:217], v[34:37]
	v_lshl_add_u32 v100, v100, 4, v146
	ds_write2st64_b64 v104, v[102:103], v[28:29] offset0:16 offset1:48
	v_cvt_pk_bf16_f32 v28, v66, v67
	v_mfma_f32_16x16x32_bf16 v[2:5], v[194:197], v[222:225], v[2:5]
	v_cvt_pk_bf16_f32 v29, v68, v69
	ds_write2st64_b64 v100, v[98:99], v[28:29] offset0:16 offset1:48
	s_nop 1
	v_cvt_pk_bf16_f32 v34, v34, v35
	v_mfma_f32_16x16x32_bf16 v[38:41], v[174:177], v[178:181], v[38:41]
	v_cvt_pk_bf16_f32 v35, v36, v37
	s_nop 0
	v_cvt_pk_bf16_f32 v2, v2, v3
	v_cvt_pk_bf16_f32 v3, v4, v5
	v_mfma_f32_16x16x32_bf16 v[6:9], v[154:157], v[178:181], v[6:9]
	ds_write2st64_b64 v104, v[34:35], v[2:3] offset0:80 offset1:112
	v_mfma_f32_16x16x32_bf16 v[28:31], v[198:201], v[214:217], v[30:33]
	v_mfma_f32_16x16x32_bf16 v[2:5], v[198:201], v[222:225], v[38:41]
	v_mfma_f32_16x16x32_bf16 v[62:65], v[186:189], v[140:143], v[62:65]
	s_nop 5
	v_cvt_pk_bf16_f32 v32, v28, v29
	v_cvt_pk_bf16_f32 v33, v30, v31
	v_cvt_pk_bf16_f32 v2, v2, v3
	v_mfma_f32_16x16x32_bf16 v[58:61], v[190:193], v[140:143], v[58:61]
	v_cvt_pk_bf16_f32 v3, v4, v5
	v_cvt_pk_bf16_f32 v62, v62, v63
	v_cvt_pk_bf16_f32 v63, v64, v65
	v_mfma_f32_16x16x32_bf16 v[54:57], v[194:197], v[140:143], v[54:57]
	ds_write2st64_b64 v100, v[32:33], v[2:3] offset0:80 offset1:112
	s_nop 2
	v_cvt_pk_bf16_f32 v58, v58, v59
	v_cvt_pk_bf16_f32 v59, v60, v61
	v_mfma_f32_16x16x32_bf16 v[50:53], v[198:201], v[140:143], v[50:53]
	v_and_b32_e32 v2, 0x1f0, v138
	v_cvt_pk_bf16_f32 v54, v54, v55
	v_cvt_pk_bf16_f32 v55, v56, v57
	v_mfma_f32_16x16x32_bf16 v[46:49], v[186:189], v[214:217], v[46:49]
	v_mfma_f32_16x16x32_bf16 v[42:45], v[190:193], v[214:217], v[42:45]
	s_nop 2
	v_cvt_pk_bf16_f32 v50, v50, v51
	v_cvt_pk_bf16_f32 v51, v52, v53
	s_nop 1
	v_cvt_pk_bf16_f32 v46, v46, v47
	v_mfma_f32_16x16x32_bf16 v[28:31], v[186:189], v[218:221], v[182:185]
	v_cvt_pk_bf16_f32 v47, v48, v49
	v_cvt_pk_bf16_f32 v42, v42, v43
	v_cvt_pk_bf16_f32 v43, v44, v45
	v_mfma_f32_16x16x32_bf16 v[22:25], v[190:193], v[218:221], v[22:25]
	v_mfma_f32_16x16x32_bf16 v[18:21], v[194:197], v[218:221], v[18:21]
	s_nop 2
	v_cvt_pk_bf16_f32 v28, v28, v29
	v_cvt_pk_bf16_f32 v29, v30, v31
	s_nop 1
	v_cvt_pk_bf16_f32 v22, v22, v23
	v_mfma_f32_16x16x32_bf16 v[14:17], v[198:201], v[218:221], v[14:17]
	v_cvt_pk_bf16_f32 v23, v24, v25
	v_cvt_pk_bf16_f32 v18, v18, v19
	v_cvt_pk_bf16_f32 v19, v20, v21
	v_mfma_f32_16x16x32_bf16 v[10:13], v[186:189], v[222:225], v[10:13]
	ds_write2st64_b64 v127, v[62:63], v[28:29] offset0:64 offset1:96
	s_nop 2
	v_cvt_pk_bf16_f32 v14, v14, v15
	v_cvt_pk_bf16_f32 v15, v16, v17
	v_mfma_f32_16x16x32_bf16 v[6:9], v[190:193], v[222:225], v[6:9]
	ds_write2st64_b64 v124, v[58:59], v[22:23] offset0:64 offset1:96
	v_cvt_pk_bf16_f32 v10, v10, v11
	v_cvt_pk_bf16_f32 v11, v12, v13
	ds_write2st64_b64 v120, v[54:55], v[18:19] offset0:64 offset1:96
	ds_write2st64_b64 v116, v[50:51], v[14:15] offset0:64 offset1:96
	s_nop 2
	v_cvt_pk_bf16_f32 v6, v6, v7
	v_cvt_pk_bf16_f32 v7, v8, v9
	ds_write2st64_b64 v112, v[46:47], v[10:11] offset0:80 offset1:112
	ds_write2st64_b64 v108, v[42:43], v[6:7] offset0:80 offset1:112
	s_waitcnt lgkmcnt(0)
	s_barrier

; #define GLDS_STAGE(st, kt_) do { \
;         _Pragma("unroll") for (int i_ = 0; i_ < FI; ++i_) { \
;             glds16(ap + (size_t)(32 * i_) * lda + (kt_) * 64, l3a + (st) + tid * 16 + i_ * 4096); \
;             glds16(bp + (size_t)(32 * i_) * ldb + (kt_) * 64, l3a + (st) + OPB + tid * 16 + i_ * 4096); } } while (0)
; #define GLDS_STAGE(st, kt_) do { \
;         _Pragma("unroll") for (int i_ = 0; i_ < 4; ++i_) { \
;             glds16(ap + (size_t)(64 * i_) * lda + (kt_) * 64, l3a + (st) + tid * 16 + i_ * 8192); \
;             glds16(bp + (size_t)(64 * i_) * ldb + (kt_) * 64, l3a + (st) + 32768 + tid * 16 + i_ * 8192); } } while (0)
; template <class Epi>
; DEV void gemm256_tile(const bf16_t* __restrict__ A, int lda, const bf16_t* __restrict__ Bt, int ldb, int K, unsigned char* lds, const Epi& epi) {
;     ...
;     for (int kt = 0; kt < nk; ++kt) {
;         const int cur = (kt & 1) * 65536;
;         asm volatile("s_waitcnt vmcnt(0)" ::: "memory");
;         __syncthreads();
;         if (kt + 1 < nk) GLDS_STAGE(cur ^ 65536, kt + 1);
; #pragma unroll
;         for (int kh = 0; kh < 2; ++kh) {
;             bf16x8 bfr[4];
;             const int ch = ((kh * 4 + fq) ^ sw) << 4;
; #pragma unroll
;             for (int i = 0; i < 4; ++i) bfr[i] = *(const bf16x8*)(lds + cur + boff + i * 2048 + ch);
; #pragma unroll
;             for (int mh = 0; mh < 2; ++mh) {
;                 bf16x8 af[4];
; #pragma unroll
;                 for (int i = 0; i < 4; ++i) af[i] = *(const bf16x8*)(lds + cur + aoff + (mh * 4 + i) * 2048 + ch);
; #pragma unroll
;                 for (int mi = 0; mi < 4; ++mi)
; #pragma unroll
;                     for (int ni = 0; ni < 4; ++ni) acc[mh * 4 + mi][ni] = __builtin_amdgcn_mfma_f32_16x16x32_bf16(bfr[ni], af[mi], acc[mh * 4 + mi][ni], 0, 0, 0);
;             }
;         }
.LBB0_1466:
	s_and_b32 s48, s21, 0x10000
	s_xor_b32 s49, s48, 0x10000
	v_add_u32_e32 v216, s49, v140
	v_add_u32_e32 v217, s49, v153
	s_waitcnt vmcnt(0) lgkmcnt(0)
	s_barrier
	v_or_b32_e32 v248, s48, v155
	v_add_u32_e32 v249, s48, v152
	v_add_u32_e32 v244, v248, v154
	v_add_u32_e32 v245, v249, v154
	ds_read_b128 v[162:165], v244 offset:32768
	ds_read_b128 v[228:231], v245
	ds_read_b128 v[166:169], v244 offset:34816
	ds_read_b128 v[170:173], v244 offset:36864
	ds_read_b128 v[174:177], v244 offset:38912
	ds_read_b128 v[232:235], v245 offset:2048
	ds_read_b128 v[236:239], v245 offset:4096
	ds_read_b128 v[240:243], v245 offset:6144
	v_readfirstlane_b32 s40, v216
	v_readfirstlane_b32 s44, v217
	v_add_u32_e32 v246, v248, v151
	v_add_u32_e32 v247, v249, v151
	s_mov_b32 m0, s40
	v_lshl_add_u64 v[204:205], v[142:143], 0, s[4:5]
	global_load_lds_dwordx4 v[142:143], off
	s_mov_b32 m0, s44
	v_lshl_add_u64 v[210:211], v[144:145], 0, s[4:5]
	global_load_lds_dwordx4 v[144:145], off
	s_add_i32 s41, s40, 0x2000
	s_add_i32 s45, s44, 0x2000
	s_add_i32 s42, s40, 0x4000
	s_add_i32 s46, s44, 0x4000
	s_add_i32 s43, s40, 0x6000
	s_add_i32 s47, s44, 0x6000
	s_add_i32 s21, s21, 0x10000
	s_waitcnt lgkmcnt(6)
	v_mfma_f32_16x16x32_bf16 v[126:129], v[162:165], v[228:231], v[126:129]
	v_lshl_add_u64 v[206:207], v[142:143], 0, s[6:7]
	s_waitcnt lgkmcnt(5)
	v_mfma_f32_16x16x32_bf16 v[122:125], v[166:169], v[228:231], v[122:125]
	v_lshl_add_u64 v[212:213], v[144:145], 0, s[6:7]
	s_waitcnt lgkmcnt(4)
	v_mfma_f32_16x16x32_bf16 v[118:121], v[170:173], v[228:231], v[118:121]
	v_lshl_add_u64 v[208:209], v[142:143], 0, s[8:9]
	s_waitcnt lgkmcnt(3)
	v_mfma_f32_16x16x32_bf16 v[114:117], v[174:177], v[228:231], v[114:117]
	v_lshl_add_u64 v[214:215], v[144:145], 0, s[8:9]
	s_waitcnt lgkmcnt(2)
	v_mfma_f32_16x16x32_bf16 v[110:113], v[162:165], v[232:235], v[110:113]
	v_mfma_f32_16x16x32_bf16 v[106:109], v[166:169], v[232:235], v[106:109]
	v_mfma_f32_16x16x32_bf16 v[102:105], v[170:173], v[232:235], v[102:105]
	v_mfma_f32_16x16x32_bf16 v[98:101], v[174:177], v[232:235], v[98:101]
	s_waitcnt lgkmcnt(1)
	v_mfma_f32_16x16x32_bf16 v[94:97], v[162:165], v[236:239], v[94:97]
	ds_read_b128 v[228:231], v245 offset:8192
	v_mfma_f32_16x16x32_bf16 v[90:93], v[166:169], v[236:239], v[90:93]
	ds_read_b128 v[232:235], v245 offset:10240
	v_mfma_f32_16x16x32_bf16 v[86:89], v[170:173], v[236:239], v[86:89]
	s_mov_b32 m0, s41
	v_mfma_f32_16x16x32_bf16 v[82:85], v[174:177], v[236:239], v[82:85]
	global_load_lds_dwordx4 v[204:205], off
	s_waitcnt lgkmcnt(2)
	v_mfma_f32_16x16x32_bf16 v[78:81], v[162:165], v[240:243], v[78:81]
	s_mov_b32 m0, s45
	v_mfma_f32_16x16x32_bf16 v[74:77], v[166:169], v[240:243], v[74:77]
	global_load_lds_dwordx4 v[210:211], off
	v_mfma_f32_16x16x32_bf16 v[70:73], v[170:173], v[240:243], v[70:73]
	v_mfma_f32_16x16x32_bf16 v[66:69], v[174:177], v[240:243], v[66:69]
	s_waitcnt lgkmcnt(1)
	v_mfma_f32_16x16x32_bf16 v[62:65], v[162:165], v[228:231], v[62:65]
	ds_read_b128 v[236:239], v245 offset:12288
	v_mfma_f32_16x16x32_bf16 v[58:61], v[166:169], v[228:231], v[58:61]
	ds_read_b128 v[240:243], v245 offset:14336
	v_mfma_f32_16x16x32_bf16 v[54:57], v[170:173], v[228:231], v[54:57]
	s_mov_b32 m0, s42
	v_mfma_f32_16x16x32_bf16 v[50:53], v[174:177], v[228:231], v[50:53]
	global_load_lds_dwordx4 v[206:207], off
	s_waitcnt lgkmcnt(2)
	v_mfma_f32_16x16x32_bf16 v[46:49], v[162:165], v[232:235], v[46:49]
	s_mov_b32 m0, s46
	v_mfma_f32_16x16x32_bf16 v[42:45], v[166:169], v[232:235], v[42:45]
	global_load_lds_dwordx4 v[212:213], off
	v_mfma_f32_16x16x32_bf16 v[34:37], v[170:173], v[232:235], v[34:37]
	v_mfma_f32_16x16x32_bf16 v[30:33], v[174:177], v[232:235], v[30:33]
	s_waitcnt lgkmcnt(1)
	v_mfma_f32_16x16x32_bf16 v[26:29], v[162:165], v[236:239], v[26:29]
	ds_read_b128 v[178:181], v246 offset:32768
	v_mfma_f32_16x16x32_bf16 v[22:25], v[166:169], v[236:239], v[22:25]
	ds_read_b128 v[182:185], v246 offset:34816
	v_mfma_f32_16x16x32_bf16 v[18:21], v[170:173], v[236:239], v[18:21]
	ds_read_b128 v[220:223], v246 offset:36864
	v_mfma_f32_16x16x32_bf16 v[14:17], v[174:177], v[236:239], v[14:17]
	ds_read_b128 v[224:227], v246 offset:38912
	s_waitcnt lgkmcnt(4)
	v_mfma_f32_16x16x32_bf16 v[10:13], v[162:165], v[240:243], v[10:13]
	ds_read_b128 v[228:231], v247
	v_mfma_f32_16x16x32_bf16 v[6:9], v[166:169], v[240:243], v[6:9]
	ds_read_b128 v[232:235], v247 offset:2048
	v_mfma_f32_16x16x32_bf16 v[2:5], v[170:173], v[240:243], v[2:5]
	s_mov_b32 m0, s43
	v_mfma_f32_16x16x32_bf16 v[38:41], v[174:177], v[240:243], v[38:41]
	global_load_lds_dwordx4 v[208:209], off
	s_mov_b32 m0, s47
	v_lshl_add_u64 v[142:143], v[142:143], 0, s[10:11]
	global_load_lds_dwordx4 v[214:215], off
	v_lshl_add_u64 v[144:145], v[144:145], 0, s[10:11]
	s_waitcnt lgkmcnt(1)
	v_mfma_f32_16x16x32_bf16 v[126:129], v[178:181], v[228:231], v[126:129]
	ds_read_b128 v[236:239], v247 offset:4096
	v_mfma_f32_16x16x32_bf16 v[122:125], v[182:185], v[228:231], v[122:125]
	ds_read_b128 v[240:243], v247 offset:6144
	v_mfma_f32_16x16x32_bf16 v[118:121], v[220:223], v[228:231], v[118:121]
	v_mfma_f32_16x16x32_bf16 v[114:117], v[224:227], v[228:231], v[114:117]
	s_waitcnt lgkmcnt(2)
	v_mfma_f32_16x16x32_bf16 v[110:113], v[178:181], v[232:235], v[110:113]
	v_mfma_f32_16x16x32_bf16 v[106:109], v[182:185], v[232:235], v[106:109]
	v_mfma_f32_16x16x32_bf16 v[102:105], v[220:223], v[232:235], v[102:105]
	v_mfma_f32_16x16x32_bf16 v[98:101], v[224:227], v[232:235], v[98:101]
	s_waitcnt lgkmcnt(1)
; #define GLDS_STAGE(st, kt_) do { \
;         _Pragma("unroll") for (int i_ = 0; i_ < FI; ++i_) { \
;             glds16(ap + (size_t)(32 * i_) * lda + (kt_) * 64, l3a + (st) + tid * 16 + i_ * 4096); \
;             glds16(bp + (size_t)(32 * i_) * ldb + (kt_) * 64, l3a + (st) + OPB + tid * 16 + i_ * 4096); } } while (0)
; #define GLDS_STAGE(st, kt_) do { \
;         _Pragma("unroll") for (int i_ = 0; i_ < 4; ++i_) { \
;             glds16(ap + (size_t)(64 * i_) * lda + (kt_) * 64, l3a + (st) + tid * 16 + i_ * 8192); \
;             glds16(bp + (size_t)(64 * i_) * ldb + (kt_) * 64, l3a + (st) + 32768 + tid * 16 + i_ * 8192); } } while (0)
; template <class Epi>
; DEV void gemm256_tile(const bf16_t* __restrict__ A, int lda, const bf16_t* __restrict__ Bt, int ldb, int K, unsigned char* lds, const Epi& epi) {
;     ...
;     for (int kt = 0; kt < nk; ++kt) {
;         const int cur = (kt & 1) * 65536;
;         asm volatile("s_waitcnt vmcnt(0)" ::: "memory");
;         __syncthreads();
;         if (kt + 1 < nk) GLDS_STAGE(cur ^ 65536, kt + 1);
; #pragma unroll
;         for (int kh = 0; kh < 2; ++kh) {
;             bf16x8 bfr[4];
;             const int ch = ((kh * 4 + fq) ^ sw) << 4;
; #pragma unroll
;             for (int i = 0; i < 4; ++i) bfr[i] = *(const bf16x8*)(lds + cur + boff + i * 2048 + ch);
; #pragma unroll
;             for (int mh = 0; mh < 2; ++mh) {
;                 bf16x8 af[4];
; #pragma unroll
;                 for (int i = 0; i < 4; ++i) af[i] = *(const bf16x8*)(lds + cur + aoff + (mh * 4 + i) * 2048 + ch);
; #pragma unroll
;                 for (int mi = 0; mi < 4; ++mi)
; #pragma unroll
;                     for (int ni = 0; ni < 4; ++ni) acc[mh * 4 + mi][ni] = __builtin_amdgcn_mfma_f32_16x16x32_bf16(bfr[ni], af[mi], acc[mh * 4 + mi][ni], 0, 0, 0);
;             }
;         }
;     }
;     ...
;     __syncthreads();
	v_mfma_f32_16x16x32_bf16 v[94:97], v[178:181], v[236:239], v[94:97]
	ds_read_b128 v[228:231], v247 offset:8192
	v_mfma_f32_16x16x32_bf16 v[90:93], v[182:185], v[236:239], v[90:93]
	ds_read_b128 v[232:235], v247 offset:10240
	v_mfma_f32_16x16x32_bf16 v[86:89], v[220:223], v[236:239], v[86:89]
	v_mfma_f32_16x16x32_bf16 v[82:85], v[224:227], v[236:239], v[82:85]
	s_waitcnt lgkmcnt(2)
	v_mfma_f32_16x16x32_bf16 v[78:81], v[178:181], v[240:243], v[78:81]
	v_mfma_f32_16x16x32_bf16 v[74:77], v[182:185], v[240:243], v[74:77]
	v_mfma_f32_16x16x32_bf16 v[70:73], v[220:223], v[240:243], v[70:73]
	v_mfma_f32_16x16x32_bf16 v[66:69], v[224:227], v[240:243], v[66:69]
	s_waitcnt lgkmcnt(1)
	v_mfma_f32_16x16x32_bf16 v[62:65], v[178:181], v[228:231], v[62:65]
	ds_read_b128 v[236:239], v247 offset:12288
	v_mfma_f32_16x16x32_bf16 v[58:61], v[182:185], v[228:231], v[58:61]
	ds_read_b128 v[240:243], v247 offset:14336
	v_mfma_f32_16x16x32_bf16 v[54:57], v[220:223], v[228:231], v[54:57]
	v_mfma_f32_16x16x32_bf16 v[50:53], v[224:227], v[228:231], v[50:53]
	s_waitcnt lgkmcnt(2)
	v_mfma_f32_16x16x32_bf16 v[46:49], v[178:181], v[232:235], v[46:49]
	v_mfma_f32_16x16x32_bf16 v[42:45], v[182:185], v[232:235], v[42:45]
	v_mfma_f32_16x16x32_bf16 v[34:37], v[220:223], v[232:235], v[34:37]
	v_mfma_f32_16x16x32_bf16 v[30:33], v[224:227], v[232:235], v[30:33]
	s_waitcnt lgkmcnt(1)
	v_mfma_f32_16x16x32_bf16 v[26:29], v[178:181], v[236:239], v[26:29]
	v_mfma_f32_16x16x32_bf16 v[22:25], v[182:185], v[236:239], v[22:25]
	v_mfma_f32_16x16x32_bf16 v[18:21], v[220:223], v[236:239], v[18:21]
	v_mfma_f32_16x16x32_bf16 v[14:17], v[224:227], v[236:239], v[14:17]
	s_waitcnt lgkmcnt(0)
	v_mfma_f32_16x16x32_bf16 v[10:13], v[178:181], v[240:243], v[10:13]
	v_mfma_f32_16x16x32_bf16 v[6:9], v[182:185], v[240:243], v[6:9]
	v_mfma_f32_16x16x32_bf16 v[2:5], v[220:223], v[240:243], v[2:5]
	v_mfma_f32_16x16x32_bf16 v[38:41], v[224:227], v[240:243], v[38:41]
	s_cmp_eq_u32 s21, 0x1f0000
	s_cbranch_scc0 .LBB0_1466
	v_or_b32_e32 v184, 0x18000, v155
	v_add_u32_e32 v156, v184, v154
	s_waitcnt vmcnt(0)
	s_barrier
	ds_read_b128 v[142:145], v156
	ds_read_b128 v[162:165], v156 offset:2048
	ds_read_b128 v[166:169], v156 offset:4096
	ds_read_b128 v[170:173], v156 offset:6144
	v_add_u32_e32 v198, 0x10000, v152
	v_add_u32_e32 v178, v198, v154
	ds_read_b128 v[152:155], v178
	s_waitcnt lgkmcnt(0)
	v_mfma_f32_16x16x32_bf16 v[126:129], v[142:145], v[152:155], v[126:129]
	s_sext_i32_i8 s14, s20
	s_lshl_b32 s20, s14, 8
	s_ashr_i32 s21, s20, 31
	v_mfma_f32_16x16x32_bf16 v[122:125], v[162:165], v[152:155], v[122:125]
	v_lshl_add_u64 v[156:157], v[134:135], 0, s[12:13]
	v_lshl_add_u64 v[182:183], v[130:131], 0, s[12:13]
	s_lshl_b64 s[12:13], s[20:21], 1
	v_mfma_f32_16x16x32_bf16 v[118:121], v[166:169], v[152:155], v[118:121]
	v_lshlrev_b32_e32 v148, 3, v148
	v_lshlrev_b32_e32 v150, 9, v150
	v_and_or_b32 v148, v148, 8, v150
	v_mfma_f32_16x16x32_bf16 v[114:117], v[170:173], v[152:155], v[114:117]
	ds_read_b128 v[152:155], v178 offset:2048
	s_waitcnt lgkmcnt(0)
	v_mfma_f32_16x16x32_bf16 v[110:113], v[142:145], v[152:155], v[110:113]
	v_mfma_f32_16x16x32_bf16 v[106:109], v[162:165], v[152:155], v[106:109]
	v_mfma_f32_16x16x32_bf16 v[102:105], v[166:169], v[152:155], v[102:105]
	v_mfma_f32_16x16x32_bf16 v[98:101], v[170:173], v[152:155], v[98:101]
	ds_read_b128 v[152:155], v178 offset:4096
	s_waitcnt lgkmcnt(0)
	v_mfma_f32_16x16x32_bf16 v[94:97], v[142:145], v[152:155], v[94:97]
	v_mfma_f32_16x16x32_bf16 v[90:93], v[162:165], v[152:155], v[90:93]
	v_mfma_f32_16x16x32_bf16 v[86:89], v[166:169], v[152:155], v[86:89]
	v_mfma_f32_16x16x32_bf16 v[82:85], v[170:173], v[152:155], v[82:85]
	ds_read_b128 v[152:155], v178 offset:6144
	s_waitcnt lgkmcnt(0)
	v_mfma_f32_16x16x32_bf16 v[78:81], v[142:145], v[152:155], v[78:81]
	v_mfma_f32_16x16x32_bf16 v[74:77], v[162:165], v[152:155], v[74:77]
	v_mfma_f32_16x16x32_bf16 v[70:73], v[166:169], v[152:155], v[70:73]
	v_mfma_f32_16x16x32_bf16 v[66:69], v[170:173], v[152:155], v[66:69]
	ds_read_b128 v[152:155], v178 offset:8192
	ds_read_b128 v[174:177], v178 offset:10240
	s_waitcnt lgkmcnt(1)
	v_mfma_f32_16x16x32_bf16 v[62:65], v[142:145], v[152:155], v[62:65]
	v_mfma_f32_16x16x32_bf16 v[58:61], v[162:165], v[152:155], v[58:61]
	v_mfma_f32_16x16x32_bf16 v[54:57], v[166:169], v[152:155], v[54:57]
	v_mfma_f32_16x16x32_bf16 v[50:53], v[170:173], v[152:155], v[50:53]
	ds_read_b128 v[152:155], v178 offset:12288
	s_waitcnt lgkmcnt(1)
	v_mfma_f32_16x16x32_bf16 v[46:49], v[142:145], v[174:177], v[46:49]
	v_mfma_f32_16x16x32_bf16 v[42:45], v[162:165], v[174:177], v[42:45]
	v_mfma_f32_16x16x32_bf16 v[34:37], v[166:169], v[174:177], v[34:37]
	v_mfma_f32_16x16x32_bf16 v[30:33], v[170:173], v[174:177], v[30:33]
	ds_read_b128 v[174:177], v178 offset:14336
	s_waitcnt lgkmcnt(1)
	v_mfma_f32_16x16x32_bf16 v[178:181], v[142:145], v[152:155], v[26:29]
	s_nop 2
	v_lshl_add_u64 v[28:29], v[156:157], 0, s[12:13]
	v_add_u32_e32 v157, v184, v151
	v_lshl_add_u64 v[26:27], v[182:183], 0, s[12:13]
	ds_read_b128 v[182:185], v157
	ds_read_b128 v[186:189], v157 offset:2048
	ds_read_b128 v[190:193], v157 offset:4096
	ds_read_b128 v[194:197], v157 offset:6144
	v_add_u32_e32 v151, v198, v151
	v_mfma_f32_16x16x32_bf16 v[22:25], v[162:165], v[152:155], v[22:25]
	v_and_b32_e32 v156, 0xc0, v146
	v_lshl_or_b32 v149, v149, 2, v156
	s_mov_b32 s12, 0
	v_mfma_f32_16x16x32_bf16 v[18:21], v[166:169], v[152:155], v[18:21]
	v_mfma_f32_16x16x32_bf16 v[14:17], v[170:173], v[152:155], v[14:17]
	ds_read_b128 v[152:155], v151
	ds_read_b128 v[198:201], v151 offset:2048
	ds_read_b128 v[202:205], v151 offset:4096
	ds_read_b128 v[206:209], v151 offset:6144
	s_waitcnt lgkmcnt(8)
	v_mfma_f32_16x16x32_bf16 v[10:13], v[142:145], v[174:177], v[10:13]
	ds_read_b128 v[142:145], v151 offset:8192
	ds_read_b128 v[210:213], v151 offset:10240
	ds_read_b128 v[214:217], v151 offset:12288
	ds_read_b128 v[218:221], v151 offset:14336
	s_waitcnt lgkmcnt(0)
	s_barrier
; DEV unsigned cvt_pk_bf16(float lo, float hi) { const f32x2_t v = {lo, hi}; const bf16x2_t b = __builtin_convertvector(v, bf16x2_t); return __builtin_bit_cast(unsigned, b); }
; template <class Epi>
; DEV void gemm256_tile(const bf16_t* __restrict__ A, int lda, const bf16_t* __restrict__ Bt, int ldb, int K, unsigned char* lds, const Epi& epi) {
;     ...
; #pragma unroll
;         for (int mi = 0; mi < 8; ++mi)
; #pragma unroll
;             for (int ni = 0; ni < 4; ++ni) {
;                 const int row = wr * 128 + mi * 16 + fr, col = wc * 64 + ni * 16 + fq * 4;
;                 const f32x4 v = epi.xform(row, col, acc[mi][ni]);
;                 uint2 w; w.x = cvt_pk_bf16(v[0], v[1]); w.y = cvt_pk_bf16(v[2], v[3]);
;                 *(uint2*)(lds + row * 512 + ((((col >> 3) ^ (row & 31)) << 4) | (((col >> 2) & 1) << 3))) = w;
;             }
;         __syncthreads();
	v_mfma_f32_16x16x32_bf16 v[2:5], v[166:169], v[174:177], v[2:5]
	v_mfma_f32_16x16x32_bf16 v[126:129], v[182:185], v[152:155], v[126:129]
	v_mfma_f32_16x16x32_bf16 v[114:117], v[194:197], v[152:155], v[114:117]
	v_mfma_f32_16x16x32_bf16 v[102:105], v[190:193], v[198:201], v[102:105]
	s_nop 5
	v_cvt_pk_bf16_f32 v126, v126, v127
	v_cvt_pk_bf16_f32 v127, v128, v129
	v_lshrrev_b32_e32 v128, 3, v149
	v_mfma_f32_16x16x32_bf16 v[34:37], v[190:193], v[210:213], v[34:37]
	v_cvt_pk_bf16_f32 v114, v114, v115
	v_cvt_pk_bf16_f32 v115, v116, v117
	v_or_b32_e32 v117, 16, v147
	v_mfma_f32_16x16x32_bf16 v[2:5], v[190:193], v[218:221], v[2:5]
	v_cvt_pk_bf16_f32 v102, v102, v103
	v_cvt_pk_bf16_f32 v103, v104, v105
	v_bitop3_b32 v104, v128, v117, 4 bitop3:0x36
	v_mfma_f32_16x16x32_bf16 v[38:41], v[170:173], v[174:177], v[38:41]
	v_lshl_add_u32 v104, v104, 4, v148
	v_cvt_pk_bf16_f32 v34, v34, v35
	v_cvt_pk_bf16_f32 v35, v36, v37
	v_mfma_f32_16x16x32_bf16 v[6:9], v[162:165], v[174:177], v[6:9]
	v_cvt_pk_bf16_f32 v2, v2, v3
	v_cvt_pk_bf16_f32 v3, v4, v5
	ds_write2st64_b64 v104, v[34:35], v[2:3] offset0:80 offset1:112
	v_mfma_f32_16x16x32_bf16 v[30:33], v[194:197], v[210:213], v[30:33]
	v_xor_b32_e32 v129, v128, v147
	v_bitop3_b32 v116, v128, v147, 6 bitop3:0x36
	v_lshl_or_b32 v129, v129, 4, v148
	v_mfma_f32_16x16x32_bf16 v[98:101], v[194:197], v[198:201], v[98:101]
	v_lshl_add_u32 v116, v116, 4, v148
	s_nop 2
	v_cvt_pk_bf16_f32 v36, v30, v31
	v_cvt_pk_bf16_f32 v37, v32, v33
	v_mfma_f32_16x16x32_bf16 v[122:125], v[186:189], v[152:155], v[122:125]
	v_mfma_f32_16x16x32_bf16 v[118:121], v[190:193], v[152:155], v[118:121]
	v_cvt_pk_bf16_f32 v98, v98, v99
	v_cvt_pk_bf16_f32 v99, v100, v101
	v_bitop3_b32 v100, v128, v117, 6 bitop3:0x36
	v_mfma_f32_16x16x32_bf16 v[110:113], v[182:185], v[198:201], v[110:113]
	s_nop 2
	v_cvt_pk_bf16_f32 v122, v122, v123
	v_cvt_pk_bf16_f32 v123, v124, v125
	v_bitop3_b32 v124, v128, v147, 2 bitop3:0x36
	v_mfma_f32_16x16x32_bf16 v[106:109], v[186:189], v[198:201], v[106:109]
	v_cvt_pk_bf16_f32 v118, v118, v119
	v_cvt_pk_bf16_f32 v119, v120, v121
	v_bitop3_b32 v120, v128, v147, 4 bitop3:0x36
	v_mfma_f32_16x16x32_bf16 v[2:5], v[194:197], v[218:221], v[38:41]
	v_cvt_pk_bf16_f32 v110, v110, v111
	v_cvt_pk_bf16_f32 v111, v112, v113
	v_bitop3_b32 v112, v128, v147, 16 bitop3:0x1e
	v_mfma_f32_16x16x32_bf16 v[94:97], v[182:185], v[202:205], v[94:97]
	v_cvt_pk_bf16_f32 v106, v106, v107
	v_cvt_pk_bf16_f32 v107, v108, v109
	v_bitop3_b32 v108, v128, v117, 2 bitop3:0x36
	v_mfma_f32_16x16x32_bf16 v[90:93], v[186:189], v[202:205], v[90:93]
	v_lshl_add_u32 v100, v100, 4, v148
	v_cvt_pk_bf16_f32 v2, v2, v3
	v_cvt_pk_bf16_f32 v3, v4, v5
	v_mfma_f32_16x16x32_bf16 v[86:89], v[190:193], v[202:205], v[86:89]
	v_lshl_add_u32 v124, v124, 4, v148
	v_lshl_add_u32 v120, v120, 4, v148
	v_lshl_or_b32 v112, v112, 4, v148
	v_mfma_f32_16x16x32_bf16 v[82:85], v[194:197], v[202:205], v[82:85]
	v_lshl_add_u32 v108, v108, 4, v148
	v_cvt_pk_bf16_f32 v94, v94, v95
	v_cvt_pk_bf16_f32 v95, v96, v97
	v_mfma_f32_16x16x32_bf16 v[78:81], v[182:185], v[206:209], v[78:81]
	v_cvt_pk_bf16_f32 v90, v90, v91
	v_cvt_pk_bf16_f32 v91, v92, v93
	v_cvt_pk_bf16_f32 v86, v86, v87
	v_mfma_f32_16x16x32_bf16 v[74:77], v[186:189], v[206:209], v[74:77]
	v_cvt_pk_bf16_f32 v87, v88, v89
	v_cvt_pk_bf16_f32 v82, v82, v83
	v_cvt_pk_bf16_f32 v83, v84, v85
	v_mfma_f32_16x16x32_bf16 v[70:73], v[190:193], v[206:209], v[70:73]
	v_cvt_pk_bf16_f32 v78, v78, v79
	v_cvt_pk_bf16_f32 v79, v80, v81
	s_nop 1
	v_cvt_pk_bf16_f32 v74, v74, v75
	v_mfma_f32_16x16x32_bf16 v[66:69], v[194:197], v[206:209], v[66:69]
	v_cvt_pk_bf16_f32 v75, v76, v77
	s_nop 0
	v_cvt_pk_bf16_f32 v70, v70, v71
	v_cvt_pk_bf16_f32 v71, v72, v73
	v_mfma_f32_16x16x32_bf16 v[62:65], v[182:185], v[142:145], v[62:65]
	ds_write2st64_b64 v100, v[36:37], v[2:3] offset0:80 offset1:112
	s_nop 1
	v_cvt_pk_bf16_f32 v66, v66, v67
	v_cvt_pk_bf16_f32 v67, v68, v69
	v_mfma_f32_16x16x32_bf16 v[58:61], v[186:189], v[142:145], v[58:61]
	v_and_b32_e32 v2, 0x1f0, v140
	s_nop 0
	v_cvt_pk_bf16_f32 v62, v62, v63
	v_cvt_pk_bf16_f32 v63, v64, v65
	v_mfma_f32_16x16x32_bf16 v[54:57], v[190:193], v[142:145], v[54:57]
	ds_write2st64_b64 v129, v[126:127], v[94:95] offset1:32
	s_nop 1
	v_cvt_pk_bf16_f32 v58, v58, v59
	v_cvt_pk_bf16_f32 v59, v60, v61
	v_mfma_f32_16x16x32_bf16 v[50:53], v[194:197], v[142:145], v[50:53]
	ds_write2st64_b64 v124, v[122:123], v[90:91] offset1:32
	s_nop 0
	v_cvt_pk_bf16_f32 v54, v54, v55
	v_cvt_pk_bf16_f32 v55, v56, v57
	v_mfma_f32_16x16x32_bf16 v[46:49], v[182:185], v[210:213], v[46:49]
	ds_write2st64_b64 v120, v[118:119], v[86:87] offset1:32
	s_nop 1
	v_cvt_pk_bf16_f32 v50, v50, v51
	v_cvt_pk_bf16_f32 v51, v52, v53
	v_mfma_f32_16x16x32_bf16 v[42:45], v[186:189], v[210:213], v[42:45]
	ds_write2st64_b64 v116, v[114:115], v[82:83] offset1:32
	s_nop 0
	v_cvt_pk_bf16_f32 v46, v46, v47
	v_cvt_pk_bf16_f32 v47, v48, v49
	v_mfma_f32_16x16x32_bf16 v[30:33], v[182:185], v[214:217], v[178:181]
	ds_write2st64_b64 v112, v[110:111], v[78:79] offset0:16 offset1:48
	s_nop 1
	v_cvt_pk_bf16_f32 v42, v42, v43
	v_cvt_pk_bf16_f32 v43, v44, v45
	v_mfma_f32_16x16x32_bf16 v[22:25], v[186:189], v[214:217], v[22:25]
	ds_write2st64_b64 v108, v[106:107], v[74:75] offset0:16 offset1:48
	s_nop 0
	v_cvt_pk_bf16_f32 v30, v30, v31
	v_cvt_pk_bf16_f32 v31, v32, v33
	v_mfma_f32_16x16x32_bf16 v[18:21], v[190:193], v[214:217], v[18:21]
	ds_write2st64_b64 v104, v[102:103], v[70:71] offset0:16 offset1:48
	s_nop 1
	v_cvt_pk_bf16_f32 v22, v22, v23
	v_cvt_pk_bf16_f32 v23, v24, v25
	v_mfma_f32_16x16x32_bf16 v[14:17], v[194:197], v[214:217], v[14:17]
	ds_write2st64_b64 v100, v[98:99], v[66:67] offset0:16 offset1:48
	s_nop 0
	v_cvt_pk_bf16_f32 v18, v18, v19
	v_cvt_pk_bf16_f32 v19, v20, v21
	v_mfma_f32_16x16x32_bf16 v[10:13], v[182:185], v[218:221], v[10:13]
	ds_write2st64_b64 v129, v[62:63], v[30:31] offset0:64 offset1:96
	s_nop 1
	v_cvt_pk_bf16_f32 v14, v14, v15
	v_cvt_pk_bf16_f32 v15, v16, v17
	v_mfma_f32_16x16x32_bf16 v[6:9], v[186:189], v[218:221], v[6:9]
	ds_write2st64_b64 v124, v[58:59], v[22:23] offset0:64 offset1:96
	s_nop 0
	v_cvt_pk_bf16_f32 v10, v10, v11
	v_cvt_pk_bf16_f32 v11, v12, v13
	ds_write2st64_b64 v120, v[54:55], v[18:19] offset0:64 offset1:96
	ds_write2st64_b64 v116, v[50:51], v[14:15] offset0:64 offset1:96
	s_nop 1
	v_cvt_pk_bf16_f32 v6, v6, v7
	v_cvt_pk_bf16_f32 v7, v8, v9
	ds_write2st64_b64 v112, v[46:47], v[10:11] offset0:80 offset1:112
	ds_write2st64_b64 v108, v[42:43], v[6:7] offset0:80 offset1:112
	s_waitcnt lgkmcnt(0)
	s_barrier
